# code placement: the six GEMM K-loop heads and the attention 2-tile loop head pinned to 64-byte boundaries (.p2align 6)
# speedup vs baseline: 1.0077x; 1.0005x over previous
; #define PG8_STAGE(bufoff, gbase, voff) do { _Pragma("unroll") for (int _i = 0; _i < 2; ++_i) \
;         __builtin_amdgcn_global_load_lds((const unsigned*)((const char*)(gbase) + (voff)[_i]), (PG8_LAS unsigned*)(lds + (bufoff) + ldsw + _i * 8192), 16, 0, 0); } while (0)
; #define PG8_LDA(dst, b, h) do { _Pragma("unroll") for (int m = 0; m < 4; ++m) _Pragma("unroll") for (int k = 0; k < 2; ++k) dst[m][k] = *(const PG8_LAS frag_t*)(lds + PG8_SA(b, h) + aoff + m * 2048 + k * 1024); } while (0)
; #define PG8_LDB(dst, b, h) do { _Pragma("unroll") for (int n = 0; n < 2; ++n) _Pragma("unroll") for (int k = 0; k < 2; ++k) dst[n][k] = *(const PG8_LAS frag_t*)(lds + PG8_SB(b, h) + boff + n * 2048 + k * 1024); } while (0)
; #define PG8_MMA(ai, bj, At, Bt) do { __builtin_amdgcn_s_setprio(1); _Pragma("unroll") for (int m = 0; m < 4; ++m) _Pragma("unroll") for (int n = 0; n < 2; ++n) _Pragma("unroll") for (int k = 0; k < 2; ++k) \
;         acc[ai][bj][m][n] = mma1v<MMAV>(Bt[n][k], At[m][k], acc[ai][bj][m][n]); __builtin_amdgcn_s_setprio(0); } while (0)
; #define PG8_WAIT_V(n) asm volatile("s_waitcnt vmcnt(" #n ")" ::: "memory")
; #define PG8_WAIT_L(n) asm volatile("s_waitcnt lgkmcnt(" #n ")" ::: "memory")
; #define PG8_BAR __builtin_amdgcn_s_barrier()
;     ...
;         const char* nA = has_next ? (const char*)g.A + (size_t)nxt.pm * tstep : cA; const char* nB = has_next ? (const char*)g.Bt + (size_t)nxt.pn * tstep : cB;
;         for (int t = 0; t < nt; t += 2) {
;             const bool last = (t == nt - 2);
;             const char* a1 = cA + (size_t)(t + 1) * kstep;
;             const char* a2 = last ? nA : cA + (size_t)(t + 2) * kstep; const char* b2 = last ? nB : cB + (size_t)(t + 2) * kstepB;
;             const char* a3 = a2 + kstep; const char* b3 = b2 + kstepB;
;             if (last && has_next) S.a_ready(nxt);
;             if constexpr (SP2) {
;             PG8_LDB(B0, 0, 0); PG8_LDB(B1, 0, 1); PG8_SCHED; PG8_LDA(At, 0, 0); PG8_STAGE(PG8_SA(1, 1), a1 + hstep, voffA);
;             PG8_WAIT_V(8); PG8_WAIT_L(0); PG8_BAR; PG8_MMA(0, 0, At, B0); PG8_MMA(0, 1, At, B1); PG8_BAR; PG8_SCHED;
;             PG8_LDA(At, 0, 1); PG8_STAGE(PG8_SB(0, 0), b2, voffB); PG8_STAGE(PG8_SB(0, 1), b2 + hstepB, voffB); PG8_STAGE(PG8_SA(0, 0), a2, voffA);
;             PG8_WAIT_V(8); PG8_WAIT_L(0); PG8_BAR; PG8_MMA(1, 0, At, B0); PG8_MMA(1, 1, At, B1); PG8_BAR; PG8_SCHED;
.LBB0_162:
	s_ashr_i32 s15, s14, 31
	s_lshl_b64 s[16:17], s[14:15], 19
	s_add_u32 s16, s0, s16
	s_addc_u32 s17, s1, s17
	s_and_b64 s[18:19], s[4:5], exec
	s_cselect_b32 s15, s17, s25
	s_cselect_b32 s49, s16, s24
	s_ashr_i32 s13, s12, 31
	s_lshl_b64 s[18:19], s[12:13], 19
	s_add_u32 s18, s34, s18
	s_addc_u32 s19, s35, s19
	s_and_b64 s[26:27], s[4:5], exec
	s_cselect_b32 s13, s19, s23
	s_cselect_b32 s50, s18, s22
	s_add_u32 s51, s22, 0x10000
	s_addc_u32 s52, s23, 0
	s_add_u32 s22, s24, 0x40080
	s_addc_u32 s23, s25, 0
	s_mov_b32 s53, -2
	s_add_u32 s24, s22, 0xfffc0080
	s_addc_u32 s25, s23, -1
	s_add_i32 s54, 0, 0x10000
	s_cmp_eq_u32 s53, 12
	s_cselect_b32 s27, s15, s25
	s_cselect_b32 s26, s49, s24
	v_add_u32_e32 v154, s54, v158
	s_cselect_b32 s25, s13, s52
	s_cselect_b32 s24, s50, s51
	s_add_i32 s56, 0, 0x14000
	ds_read_b128 v[142:145], v154
	ds_read_b128 v[146:149], v154 offset:1024
	ds_read_b128 v[150:153], v154 offset:2048
	ds_read_b128 v[174:177], v154 offset:3072
	v_add_u32_e32 v154, s56, v158
	ds_read_b128 v[178:181], v154
	ds_read_b128 v[182:185], v154 offset:1024
	ds_read_b128 v[186:189], v154 offset:2048
	ds_read_b128 v[216:219], v154 offset:3072
	v_lshl_add_u64 v[156:157], s[22:23], 0, v[138:139]
	s_add_i32 m0, s36, 0xc000
	ds_read_b128 v[220:223], v159
	ds_read_b128 v[224:227], v159 offset:1024
	ds_read_b128 v[228:231], v159 offset:2048
	ds_read_b128 v[232:235], v159 offset:3072
	ds_read_b128 v[236:239], v159 offset:4096
	ds_read_b128 v[240:243], v159 offset:5120
	ds_read_b128 v[244:247], v159 offset:6144
	ds_read_b128 v[248:251], v159 offset:7168
	global_load_lds_dwordx4 v[156:157], off
	v_lshl_add_u64 v[156:157], s[22:23], 0, v[140:141]
	s_add_i32 m0, s36, 0xe000
	s_nop 0
	global_load_lds_dwordx4 v[156:157], off
	s_waitcnt vmcnt(16)
	s_waitcnt lgkmcnt(0)
	s_barrier
	s_setprio 1
	s_waitcnt lgkmcnt(0)
	v_mfma_i32_16x16x64_i8 v[126:129], v[142:145], v[220:223], 0
	v_mfma_i32_16x16x64_i8 v[118:121], v[150:153], v[220:223], 0
	v_mfma_i32_16x16x64_i8 v[110:113], v[142:145], v[228:231], 0
	v_mfma_i32_16x16x64_i8 v[102:105], v[150:153], v[228:231], 0
	v_mfma_i32_16x16x64_i8 v[94:97], v[142:145], v[236:239], 0
	v_mfma_i32_16x16x64_i8 v[86:89], v[150:153], v[236:239], 0
	v_mfma_i32_16x16x64_i8 v[78:81], v[142:145], v[244:247], 0
	v_mfma_i32_16x16x64_i8 v[70:73], v[150:153], v[244:247], 0
	v_mfma_i32_16x16x64_i8 v[126:129], v[146:149], v[224:227], v[126:129]
	v_mfma_i32_16x16x64_i8 v[118:121], v[174:177], v[224:227], v[118:121]
	v_mfma_i32_16x16x64_i8 v[110:113], v[146:149], v[232:235], v[110:113]
	v_mfma_i32_16x16x64_i8 v[102:105], v[174:177], v[232:235], v[102:105]
	v_mfma_i32_16x16x64_i8 v[94:97], v[146:149], v[240:243], v[94:97]
	v_mfma_i32_16x16x64_i8 v[86:89], v[174:177], v[240:243], v[86:89]
	v_mfma_i32_16x16x64_i8 v[78:81], v[146:149], v[248:251], v[78:81]
	v_mfma_i32_16x16x64_i8 v[70:73], v[174:177], v[248:251], v[70:73]
	s_setprio 0
	s_setprio 1
	v_mfma_i32_16x16x64_i8 v[122:125], v[178:181], v[220:223], 0
	v_mfma_i32_16x16x64_i8 v[114:117], v[186:189], v[220:223], 0
	v_mfma_i32_16x16x64_i8 v[106:109], v[178:181], v[228:231], 0
	v_mfma_i32_16x16x64_i8 v[98:101], v[186:189], v[228:231], 0
	v_mfma_i32_16x16x64_i8 v[90:93], v[178:181], v[236:239], 0
	v_mfma_i32_16x16x64_i8 v[82:85], v[186:189], v[236:239], 0
	v_mfma_i32_16x16x64_i8 v[74:77], v[178:181], v[244:247], 0
	v_mfma_i32_16x16x64_i8 v[66:69], v[186:189], v[244:247], 0
	v_mfma_i32_16x16x64_i8 v[122:125], v[182:185], v[224:227], v[122:125]
	v_mfma_i32_16x16x64_i8 v[114:117], v[216:219], v[224:227], v[114:117]
	v_mfma_i32_16x16x64_i8 v[106:109], v[182:185], v[232:235], v[106:109]
	v_mfma_i32_16x16x64_i8 v[98:101], v[216:219], v[232:235], v[98:101]
	v_mfma_i32_16x16x64_i8 v[90:93], v[182:185], v[240:243], v[90:93]
	v_mfma_i32_16x16x64_i8 v[82:85], v[216:219], v[240:243], v[82:85]
	v_mfma_i32_16x16x64_i8 v[74:77], v[182:185], v[248:251], v[74:77]
	v_mfma_i32_16x16x64_i8 v[66:69], v[216:219], v[248:251], v[66:69]
	s_setprio 0
	s_barrier
	s_add_i32 s54, s54, s31
	v_lshl_add_u64 v[156:157], s[24:25], 0, v[134:135]
	s_mov_b32 m0, s54
	ds_read_b128 v[220:223], v159 offset:16384
	ds_read_b128 v[224:227], v159 offset:17408
	ds_read_b128 v[228:231], v159 offset:18432
	ds_read_b128 v[232:235], v159 offset:19456
	ds_read_b128 v[236:239], v159 offset:20480
	ds_read_b128 v[240:243], v159 offset:21504
	ds_read_b128 v[244:247], v159 offset:22528
	ds_read_b128 v[248:251], v159 offset:23552
	global_load_lds_dwordx4 v[156:157], off
	s_add_i32 m0, s54, 0x2000
	s_add_u32 s54, s24, 0x4000
	v_lshl_add_u64 v[156:157], s[24:25], 0, v[130:131]
	s_addc_u32 s55, s25, 0
	s_add_i32 s56, s56, s31
	global_load_lds_dwordx4 v[156:157], off
	v_lshl_add_u64 v[156:157], s[54:55], 0, v[134:135]
	s_mov_b32 m0, s56
	v_lshl_add_u64 v[160:161], s[26:27], 0, v[132:133]
	global_load_lds_dwordx4 v[156:157], off
	v_lshl_add_u64 v[156:157], s[54:55], 0, v[130:131]
	s_add_i32 m0, s56, 0x2000
	s_nop 0
	global_load_lds_dwordx4 v[156:157], off
	v_lshl_add_u64 v[156:157], s[26:27], 0, v[136:137]
	s_mov_b32 m0, s36
	s_nop 0
	global_load_lds_dwordx4 v[156:157], off
	s_mov_b32 m0, s37
	s_nop 0
	global_load_lds_dwordx4 v[160:161], off
	s_waitcnt vmcnt(16)
	s_waitcnt lgkmcnt(0)
	s_barrier
; #define PG8_STAGE(bufoff, gbase, voff) do { _Pragma("unroll") for (int _i = 0; _i < 2; ++_i) \
;         __builtin_amdgcn_global_load_lds((const unsigned*)((const char*)(gbase) + (voff)[_i]), (PG8_LAS unsigned*)(lds + (bufoff) + ldsw + _i * 8192), 16, 0, 0); } while (0)
; #define PG8_LDA(dst, b, h) do { _Pragma("unroll") for (int m = 0; m < 4; ++m) _Pragma("unroll") for (int k = 0; k < 2; ++k) dst[m][k] = *(const PG8_LAS frag_t*)(lds + PG8_SA(b, h) + aoff + m * 2048 + k * 1024); } while (0)
; #define PG8_LDB(dst, b, h) do { _Pragma("unroll") for (int n = 0; n < 2; ++n) _Pragma("unroll") for (int k = 0; k < 2; ++k) dst[n][k] = *(const PG8_LAS frag_t*)(lds + PG8_SB(b, h) + boff + n * 2048 + k * 1024); } while (0)
; #define PG8_MMA(ai, bj, At, Bt) do { __builtin_amdgcn_s_setprio(1); _Pragma("unroll") for (int m = 0; m < 4; ++m) _Pragma("unroll") for (int n = 0; n < 2; ++n) _Pragma("unroll") for (int k = 0; k < 2; ++k) \
;         acc[ai][bj][m][n] = mma1v<MMAV>(Bt[n][k], At[m][k], acc[ai][bj][m][n]); __builtin_amdgcn_s_setprio(0); } while (0)
; #define PG8_WAIT_V(n) asm volatile("s_waitcnt vmcnt(" #n ")" ::: "memory")
; #define PG8_WAIT_L(n) asm volatile("s_waitcnt lgkmcnt(" #n ")" ::: "memory")
; #define PG8_BAR __builtin_amdgcn_s_barrier()
; #define PG8_SCHED __builtin_amdgcn_sched_barrier(0)
;     ...
;             PG8_WAIT_V(8); PG8_WAIT_L(0); PG8_BAR; PG8_MMA(1, 0, At, B0); PG8_MMA(1, 1, At, B1); PG8_BAR; PG8_SCHED;
;             PG8_LDB(B0, 1, 0); PG8_LDB(B1, 1, 1); PG8_SCHED; PG8_LDA(At, 1, 0); PG8_STAGE(PG8_SA(0, 1), a2 + hstep, voffA);
;             PG8_WAIT_V(8); PG8_WAIT_L(0); PG8_BAR; PG8_MMA(0, 0, At, B0); PG8_MMA(0, 1, At, B1); PG8_BAR; PG8_SCHED;
	s_setprio 1
	s_waitcnt lgkmcnt(0)
	v_mfma_i32_16x16x64_i8 v[62:65], v[142:145], v[220:223], 0
	v_mfma_i32_16x16x64_i8 v[54:57], v[150:153], v[220:223], 0
	v_mfma_i32_16x16x64_i8 v[46:49], v[142:145], v[228:231], 0
	v_mfma_i32_16x16x64_i8 v[38:41], v[150:153], v[228:231], 0
	v_mfma_i32_16x16x64_i8 v[30:33], v[142:145], v[236:239], 0
	v_mfma_i32_16x16x64_i8 v[22:25], v[150:153], v[236:239], 0
	v_mfma_i32_16x16x64_i8 v[14:17], v[142:145], v[244:247], 0
	v_mfma_i32_16x16x64_i8 v[6:9], v[150:153], v[244:247], 0
	v_mfma_i32_16x16x64_i8 v[62:65], v[146:149], v[224:227], v[62:65]
	v_mfma_i32_16x16x64_i8 v[54:57], v[174:177], v[224:227], v[54:57]
	v_mfma_i32_16x16x64_i8 v[46:49], v[146:149], v[232:235], v[46:49]
	v_mfma_i32_16x16x64_i8 v[38:41], v[174:177], v[232:235], v[38:41]
	v_mfma_i32_16x16x64_i8 v[30:33], v[146:149], v[240:243], v[30:33]
	v_mfma_i32_16x16x64_i8 v[22:25], v[174:177], v[240:243], v[22:25]
	v_mfma_i32_16x16x64_i8 v[14:17], v[146:149], v[248:251], v[14:17]
	v_mfma_i32_16x16x64_i8 v[6:9], v[174:177], v[248:251], v[6:9]
	s_setprio 0
	s_setprio 1
	v_mfma_i32_16x16x64_i8 v[58:61], v[178:181], v[220:223], 0
	v_mfma_i32_16x16x64_i8 v[50:53], v[186:189], v[220:223], 0
	v_mfma_i32_16x16x64_i8 v[42:45], v[178:181], v[228:231], 0
	v_mfma_i32_16x16x64_i8 v[34:37], v[186:189], v[228:231], 0
	v_mfma_i32_16x16x64_i8 v[26:29], v[178:181], v[236:239], 0
	v_mfma_i32_16x16x64_i8 v[18:21], v[186:189], v[236:239], 0
	v_mfma_i32_16x16x64_i8 v[10:13], v[178:181], v[244:247], 0
	v_mfma_i32_16x16x64_i8 v[2:5], v[186:189], v[244:247], 0
	v_mfma_i32_16x16x64_i8 v[58:61], v[182:185], v[224:227], v[58:61]
	v_mfma_i32_16x16x64_i8 v[50:53], v[216:219], v[224:227], v[50:53]
	v_mfma_i32_16x16x64_i8 v[42:45], v[182:185], v[232:235], v[42:45]
	v_mfma_i32_16x16x64_i8 v[34:37], v[216:219], v[232:235], v[34:37]
	v_mfma_i32_16x16x64_i8 v[26:29], v[182:185], v[240:243], v[26:29]
	v_mfma_i32_16x16x64_i8 v[18:21], v[216:219], v[240:243], v[18:21]
	v_mfma_i32_16x16x64_i8 v[10:13], v[182:185], v[248:251], v[10:13]
	v_mfma_i32_16x16x64_i8 v[2:5], v[216:219], v[248:251], v[2:5]
	s_setprio 0
	s_barrier
	s_add_i32 s54, 0, 0x18000
	v_add_u32_e32 v154, s54, v158
	s_add_i32 s55, 0, 0x1c000
	ds_read_b128 v[142:145], v154
	ds_read_b128 v[146:149], v154 offset:1024
	ds_read_b128 v[150:153], v154 offset:2048
	ds_read_b128 v[174:177], v154 offset:3072
	v_add_u32_e32 v154, s55, v158
	ds_read_b128 v[178:181], v154
	ds_read_b128 v[182:185], v154 offset:1024
	ds_read_b128 v[186:189], v154 offset:2048
	ds_read_b128 v[216:219], v154 offset:3072
	s_add_u32 s26, s26, 0x40000
	s_addc_u32 s27, s27, 0
	s_mov_b32 m0, s38
	v_lshl_add_u64 v[190:191], s[26:27], 0, v[136:137]
	ds_read_b128 v[220:223], v159 offset:32768
	ds_read_b128 v[224:227], v159 offset:33792
	ds_read_b128 v[228:231], v159 offset:34816
	ds_read_b128 v[232:235], v159 offset:35840
	ds_read_b128 v[236:239], v159 offset:36864
	ds_read_b128 v[240:243], v159 offset:37888
	ds_read_b128 v[244:247], v159 offset:38912
	ds_read_b128 v[248:251], v159 offset:39936
	global_load_lds_dwordx4 v[190:191], off
	v_lshl_add_u64 v[190:191], s[26:27], 0, v[132:133]
	s_mov_b32 m0, s39
	s_nop 0
	global_load_lds_dwordx4 v[190:191], off
	s_waitcnt vmcnt(8)
	s_waitcnt lgkmcnt(0)
	s_barrier
	s_setprio 1
	s_waitcnt lgkmcnt(0)
	v_mfma_i32_16x16x64_i8 v[126:129], v[142:145], v[220:223], v[126:129]
	v_mfma_i32_16x16x64_i8 v[118:121], v[150:153], v[220:223], v[118:121]
	v_mfma_i32_16x16x64_i8 v[110:113], v[142:145], v[228:231], v[110:113]
	v_mfma_i32_16x16x64_i8 v[102:105], v[150:153], v[228:231], v[102:105]
	v_mfma_i32_16x16x64_i8 v[94:97], v[142:145], v[236:239], v[94:97]
	v_mfma_i32_16x16x64_i8 v[86:89], v[150:153], v[236:239], v[86:89]
	v_mfma_i32_16x16x64_i8 v[78:81], v[142:145], v[244:247], v[78:81]
	v_mfma_i32_16x16x64_i8 v[70:73], v[150:153], v[244:247], v[70:73]
	v_mfma_i32_16x16x64_i8 v[126:129], v[146:149], v[224:227], v[126:129]
	v_mfma_i32_16x16x64_i8 v[118:121], v[174:177], v[224:227], v[118:121]
	v_mfma_i32_16x16x64_i8 v[110:113], v[146:149], v[232:235], v[110:113]
	v_mfma_i32_16x16x64_i8 v[102:105], v[174:177], v[232:235], v[102:105]
	v_mfma_i32_16x16x64_i8 v[94:97], v[146:149], v[240:243], v[94:97]
	v_mfma_i32_16x16x64_i8 v[86:89], v[174:177], v[240:243], v[86:89]
	v_mfma_i32_16x16x64_i8 v[78:81], v[146:149], v[248:251], v[78:81]
	v_mfma_i32_16x16x64_i8 v[70:73], v[174:177], v[248:251], v[70:73]
	s_setprio 0
	s_setprio 1
	v_mfma_i32_16x16x64_i8 v[122:125], v[178:181], v[220:223], v[122:125]
	v_mfma_i32_16x16x64_i8 v[114:117], v[186:189], v[220:223], v[114:117]
	v_mfma_i32_16x16x64_i8 v[106:109], v[178:181], v[228:231], v[106:109]
	v_mfma_i32_16x16x64_i8 v[98:101], v[186:189], v[228:231], v[98:101]
	v_mfma_i32_16x16x64_i8 v[90:93], v[178:181], v[236:239], v[90:93]
	v_mfma_i32_16x16x64_i8 v[82:85], v[186:189], v[236:239], v[82:85]
	v_mfma_i32_16x16x64_i8 v[74:77], v[178:181], v[244:247], v[74:77]
	v_mfma_i32_16x16x64_i8 v[66:69], v[186:189], v[244:247], v[66:69]
	v_mfma_i32_16x16x64_i8 v[122:125], v[182:185], v[224:227], v[122:125]
	v_mfma_i32_16x16x64_i8 v[114:117], v[216:219], v[224:227], v[114:117]
	v_mfma_i32_16x16x64_i8 v[106:109], v[182:185], v[232:235], v[106:109]
	v_mfma_i32_16x16x64_i8 v[98:101], v[216:219], v[232:235], v[98:101]
	v_mfma_i32_16x16x64_i8 v[90:93], v[182:185], v[240:243], v[90:93]
	v_mfma_i32_16x16x64_i8 v[82:85], v[216:219], v[240:243], v[82:85]
	v_mfma_i32_16x16x64_i8 v[74:77], v[182:185], v[248:251], v[74:77]
	v_mfma_i32_16x16x64_i8 v[66:69], v[216:219], v[248:251], v[66:69]
	s_setprio 0
	s_barrier
; #define PG8_STAGE(bufoff, gbase, voff) do { _Pragma("unroll") for (int _i = 0; _i < 2; ++_i) \
;         __builtin_amdgcn_global_load_lds((const unsigned*)((const char*)(gbase) + (voff)[_i]), (PG8_LAS unsigned*)(lds + (bufoff) + ldsw + _i * 8192), 16, 0, 0); } while (0)
; #define PG8_LDA(dst, b, h) do { _Pragma("unroll") for (int m = 0; m < 4; ++m) _Pragma("unroll") for (int k = 0; k < 2; ++k) dst[m][k] = *(const PG8_LAS frag_t*)(lds + PG8_SA(b, h) + aoff + m * 2048 + k * 1024); } while (0)
; #define PG8_MMA(ai, bj, At, Bt) do { __builtin_amdgcn_s_setprio(1); _Pragma("unroll") for (int m = 0; m < 4; ++m) _Pragma("unroll") for (int n = 0; n < 2; ++n) _Pragma("unroll") for (int k = 0; k < 2; ++k) \
;         acc[ai][bj][m][n] = mma1v<MMAV>(Bt[n][k], At[m][k], acc[ai][bj][m][n]); __builtin_amdgcn_s_setprio(0); } while (0)
; #define PG8_WAIT_V(n) asm volatile("s_waitcnt vmcnt(" #n ")" ::: "memory")
; #define PG8_WAIT_L(n) asm volatile("s_waitcnt lgkmcnt(" #n ")" ::: "memory")
; #define PG8_BAR __builtin_amdgcn_s_barrier()
; #define PG8_SCHED __builtin_amdgcn_sched_barrier(0)
;     ...
;         for (int t = 0; t < nt; t += 2) {
;     ...
;             PG8_LDA(At, 1, 1); PG8_STAGE(PG8_SB(1, 0), b3, voffB); PG8_STAGE(PG8_SB(1, 1), b3 + hstepB, voffB); PG8_STAGE(PG8_SA(1, 0), a3, voffA);
;             PG8_WAIT_V(8); PG8_WAIT_L(0); PG8_BAR; PG8_MMA(1, 0, At, B0); PG8_MMA(1, 1, At, B1); PG8_BAR; PG8_SCHED;
	s_add_u32 s26, s24, 0x8000
	s_addc_u32 s27, s25, 0
	s_add_i32 s54, s54, s31
	v_lshl_add_u64 v[190:191], s[26:27], 0, v[134:135]
	s_mov_b32 m0, s54
	ds_read_b128 v[220:223], v159 offset:49152
	ds_read_b128 v[224:227], v159 offset:50176
	ds_read_b128 v[228:231], v159 offset:51200
	ds_read_b128 v[232:235], v159 offset:52224
	ds_read_b128 v[236:239], v159 offset:53248
	ds_read_b128 v[240:243], v159 offset:54272
	ds_read_b128 v[244:247], v159 offset:55296
	ds_read_b128 v[248:251], v159 offset:56320
	global_load_lds_dwordx4 v[190:191], off
	s_add_i32 m0, s54, 0x2000
	s_add_u32 s24, s24, 0xc000
	v_lshl_add_u64 v[190:191], s[26:27], 0, v[130:131]
	s_addc_u32 s25, s25, 0
	s_add_i32 s26, s55, s31
	global_load_lds_dwordx4 v[190:191], off
	v_lshl_add_u64 v[190:191], s[24:25], 0, v[134:135]
	s_mov_b32 m0, s26
	v_lshl_add_u64 v[156:157], v[156:157], 0, s[78:79]
	global_load_lds_dwordx4 v[190:191], off
	v_lshl_add_u64 v[190:191], s[24:25], 0, v[130:131]
	s_add_i32 m0, s26, 0x2000
	s_nop 0
	global_load_lds_dwordx4 v[190:191], off
	s_mov_b32 m0, s42
	s_nop 0
	global_load_lds_dwordx4 v[156:157], off
	v_lshl_add_u64 v[156:157], v[160:161], 0, s[78:79]
	s_mov_b32 m0, s43
	s_nop 0
	global_load_lds_dwordx4 v[156:157], off
	s_waitcnt vmcnt(8)
	s_waitcnt lgkmcnt(0)
	s_barrier
	s_setprio 1
	s_waitcnt lgkmcnt(0)
	v_mfma_i32_16x16x64_i8 v[62:65], v[142:145], v[220:223], v[62:65]
	v_mfma_i32_16x16x64_i8 v[54:57], v[150:153], v[220:223], v[54:57]
	v_mfma_i32_16x16x64_i8 v[46:49], v[142:145], v[228:231], v[46:49]
	v_mfma_i32_16x16x64_i8 v[38:41], v[150:153], v[228:231], v[38:41]
	v_mfma_i32_16x16x64_i8 v[30:33], v[142:145], v[236:239], v[30:33]
	v_mfma_i32_16x16x64_i8 v[22:25], v[150:153], v[236:239], v[22:25]
	v_mfma_i32_16x16x64_i8 v[14:17], v[142:145], v[244:247], v[14:17]
	v_mfma_i32_16x16x64_i8 v[6:9], v[150:153], v[244:247], v[6:9]
	v_mfma_i32_16x16x64_i8 v[62:65], v[146:149], v[224:227], v[62:65]
	v_mfma_i32_16x16x64_i8 v[54:57], v[174:177], v[224:227], v[54:57]
	v_mfma_i32_16x16x64_i8 v[46:49], v[146:149], v[232:235], v[46:49]
	v_mfma_i32_16x16x64_i8 v[38:41], v[174:177], v[232:235], v[38:41]
	v_mfma_i32_16x16x64_i8 v[30:33], v[146:149], v[240:243], v[30:33]
	v_mfma_i32_16x16x64_i8 v[22:25], v[174:177], v[240:243], v[22:25]
	v_mfma_i32_16x16x64_i8 v[14:17], v[146:149], v[248:251], v[14:17]
	v_mfma_i32_16x16x64_i8 v[6:9], v[174:177], v[248:251], v[6:9]
	s_setprio 0
	s_setprio 1
	v_mfma_i32_16x16x64_i8 v[58:61], v[178:181], v[220:223], v[58:61]
	v_mfma_i32_16x16x64_i8 v[50:53], v[186:189], v[220:223], v[50:53]
	v_mfma_i32_16x16x64_i8 v[42:45], v[178:181], v[228:231], v[42:45]
	v_mfma_i32_16x16x64_i8 v[34:37], v[186:189], v[228:231], v[34:37]
	v_mfma_i32_16x16x64_i8 v[26:29], v[178:181], v[236:239], v[26:29]
	v_mfma_i32_16x16x64_i8 v[18:21], v[186:189], v[236:239], v[18:21]
	v_mfma_i32_16x16x64_i8 v[10:13], v[178:181], v[244:247], v[10:13]
	v_mfma_i32_16x16x64_i8 v[2:5], v[186:189], v[244:247], v[2:5]
	v_mfma_i32_16x16x64_i8 v[58:61], v[182:185], v[224:227], v[58:61]
	v_mfma_i32_16x16x64_i8 v[50:53], v[216:219], v[224:227], v[50:53]
	v_mfma_i32_16x16x64_i8 v[42:45], v[182:185], v[232:235], v[42:45]
	v_mfma_i32_16x16x64_i8 v[34:37], v[216:219], v[232:235], v[34:37]
	v_mfma_i32_16x16x64_i8 v[26:29], v[182:185], v[240:243], v[26:29]
	v_mfma_i32_16x16x64_i8 v[18:21], v[216:219], v[240:243], v[18:21]
	v_mfma_i32_16x16x64_i8 v[10:13], v[182:185], v[248:251], v[10:13]
	v_mfma_i32_16x16x64_i8 v[2:5], v[216:219], v[248:251], v[2:5]
	s_setprio 0
	s_barrier
	s_add_i32 s53, s53, 2
	s_add_u32 s51, s51, 0x10000
	s_addc_u32 s52, s52, 0
	s_add_u32 s22, s22, 0x100
	s_addc_u32 s23, s23, 0
	.p2align	6

; #define PG8_STAGE(bufoff, gbase, voff) do { _Pragma("unroll") for (int _i = 0; _i < 2; ++_i) \
;         __builtin_amdgcn_global_load_lds((const unsigned*)((const char*)(gbase) + (voff)[_i]), (PG8_LAS unsigned*)(lds + (bufoff) + ldsw + _i * 8192), 16, 0, 0); } while (0)
; #define PG8_LDA(dst, b, h) do { _Pragma("unroll") for (int m = 0; m < 4; ++m) _Pragma("unroll") for (int k = 0; k < 2; ++k) dst[m][k] = *(const PG8_LAS frag_t*)(lds + PG8_SA(b, h) + aoff + m * 2048 + k * 1024); } while (0)
; #define PG8_LDB(dst, b, h) do { _Pragma("unroll") for (int n = 0; n < 2; ++n) _Pragma("unroll") for (int k = 0; k < 2; ++k) dst[n][k] = *(const PG8_LAS frag_t*)(lds + PG8_SB(b, h) + boff + n * 2048 + k * 1024); } while (0)
; #define PG8_MMA(ai, bj, At, Bt) do { __builtin_amdgcn_s_setprio(1); _Pragma("unroll") for (int m = 0; m < 4; ++m) _Pragma("unroll") for (int n = 0; n < 2; ++n) _Pragma("unroll") for (int k = 0; k < 2; ++k) \
;         acc[ai][bj][m][n] = mma1v<MMAV>(Bt[n][k], At[m][k], acc[ai][bj][m][n]); __builtin_amdgcn_s_setprio(0); } while (0)
; #define PG8_WAIT_V(n) asm volatile("s_waitcnt vmcnt(" #n ")" ::: "memory")
; #define PG8_WAIT_L(n) asm volatile("s_waitcnt lgkmcnt(" #n ")" ::: "memory")
; #define PG8_BAR __builtin_amdgcn_s_barrier()
;     ...
;         const char* nA = has_next ? (const char*)g.A + (size_t)nxt.pm * tstep : cA; const char* nB = has_next ? (const char*)g.Bt + (size_t)nxt.pn * tstep : cB;
;         for (int t = 0; t < nt; t += 2) {
;             const bool last = (t == nt - 2);
;             const char* a1 = cA + (size_t)(t + 1) * kstep;
;             const char* a2 = last ? nA : cA + (size_t)(t + 2) * kstep; const char* b2 = last ? nB : cB + (size_t)(t + 2) * kstepB;
;             const char* a3 = a2 + kstep; const char* b3 = b2 + kstepB;
;             if (last && has_next) S.a_ready(nxt);
;             if constexpr (SP2) {
;             PG8_LDB(B0, 0, 0); PG8_LDB(B1, 0, 1); PG8_SCHED; PG8_LDA(At, 0, 0); PG8_STAGE(PG8_SA(1, 1), a1 + hstep, voffA);
;             PG8_WAIT_V(8); PG8_WAIT_L(0); PG8_BAR; PG8_MMA(0, 0, At, B0); PG8_MMA(0, 1, At, B1); PG8_BAR; PG8_SCHED;
;             PG8_LDA(At, 0, 1); PG8_STAGE(PG8_SB(0, 0), b2, voffB); PG8_STAGE(PG8_SB(0, 1), b2 + hstepB, voffB); PG8_STAGE(PG8_SA(0, 0), a2, voffA);
;             PG8_WAIT_V(8); PG8_WAIT_L(0); PG8_BAR; PG8_MMA(1, 0, At, B0); PG8_MMA(1, 1, At, B1); PG8_BAR; PG8_SCHED;
.LBB0_247:
	s_add_u32 s6, s24, 0xc000
	s_addc_u32 s7, s25, 0
	s_add_u32 s53, s8, 0x10000
	s_addc_u32 s54, s9, 0
	s_mov_b32 s55, -2
	s_waitcnt lgkmcnt(0)
	s_add_u32 s8, s6, 0x4000
	s_addc_u32 s9, s7, 0
	s_cmpk_eq_i32 s55, 0x54
	s_cselect_b32 s26, s20, s8
	s_cselect_b32 s27, s21, s9
	s_cselect_b32 s24, s22, s53
	s_cselect_b32 s25, s23, s54
	s_add_u32 s8, s26, 0x8000
	s_addc_u32 s9, s27, 0
	s_add_i32 s56, 0, 0x10000
	s_add_i32 s58, 0, 0x14000
	v_add_u32_e32 v142, s56, v216
	v_add_u32_e32 v158, s58, v216
	ds_read_b128 v[130:133], v142
	ds_read_b128 v[134:137], v142 offset:1024
	ds_read_b128 v[138:141], v142 offset:2048
	ds_read_b128 v[142:145], v142 offset:3072
	ds_read_b128 v[146:149], v158
	ds_read_b128 v[150:153], v158 offset:1024
	ds_read_b128 v[154:157], v158 offset:2048
	ds_read_b128 v[158:161], v158 offset:3072
	v_lshl_add_u64 v[242:243], s[6:7], 0, v[180:181]
	s_add_i32 m0, s37, 0xc000
	ds_read_b128 v[184:187], v217
	ds_read_b128 v[188:191], v217 offset:1024
	ds_read_b128 v[218:221], v217 offset:2048
	ds_read_b128 v[222:225], v217 offset:3072
	ds_read_b128 v[226:229], v217 offset:4096
	ds_read_b128 v[230:233], v217 offset:5120
	ds_read_b128 v[234:237], v217 offset:6144
	ds_read_b128 v[238:241], v217 offset:7168
	global_load_lds_dwordx4 v[242:243], off
	v_lshl_add_u64 v[242:243], s[6:7], 0, v[182:183]
	s_add_i32 m0, s37, 0xe000
	s_nop 0
	global_load_lds_dwordx4 v[242:243], off
	s_waitcnt vmcnt(24)
	s_waitcnt lgkmcnt(0)
	s_barrier
	s_setprio 1
	s_waitcnt lgkmcnt(0)
	v_mfma_f32_16x16x32_bf16 v[126:129], v[130:133], v[184:187], 0
	v_mfma_f32_16x16x32_bf16 v[122:125], v[138:141], v[184:187], 0
	v_mfma_f32_16x16x32_bf16 v[110:113], v[130:133], v[218:221], 0
	v_mfma_f32_16x16x32_bf16 v[106:109], v[138:141], v[218:221], 0
	v_mfma_f32_16x16x32_bf16 v[94:97], v[130:133], v[226:229], 0
	v_mfma_f32_16x16x32_bf16 v[90:93], v[138:141], v[226:229], 0
	v_mfma_f32_16x16x32_bf16 v[78:81], v[130:133], v[234:237], 0
	v_mfma_f32_16x16x32_bf16 v[74:77], v[138:141], v[234:237], 0
	v_mfma_f32_16x16x32_bf16 v[126:129], v[134:137], v[188:191], v[126:129]
	v_mfma_f32_16x16x32_bf16 v[122:125], v[142:145], v[188:191], v[122:125]
	v_mfma_f32_16x16x32_bf16 v[110:113], v[134:137], v[222:225], v[110:113]
	v_mfma_f32_16x16x32_bf16 v[106:109], v[142:145], v[222:225], v[106:109]
	v_mfma_f32_16x16x32_bf16 v[94:97], v[134:137], v[230:233], v[94:97]
	v_mfma_f32_16x16x32_bf16 v[90:93], v[142:145], v[230:233], v[90:93]
	v_mfma_f32_16x16x32_bf16 v[78:81], v[134:137], v[238:241], v[78:81]
	v_mfma_f32_16x16x32_bf16 v[74:77], v[142:145], v[238:241], v[74:77]
	s_setprio 0
	s_setprio 1
	v_mfma_f32_16x16x32_bf16 v[118:121], v[146:149], v[184:187], 0
	v_mfma_f32_16x16x32_bf16 v[114:117], v[154:157], v[184:187], 0
	v_mfma_f32_16x16x32_bf16 v[102:105], v[146:149], v[218:221], 0
	v_mfma_f32_16x16x32_bf16 v[98:101], v[154:157], v[218:221], 0
	v_mfma_f32_16x16x32_bf16 v[86:89], v[146:149], v[226:229], 0
	v_mfma_f32_16x16x32_bf16 v[82:85], v[154:157], v[226:229], 0
	v_mfma_f32_16x16x32_bf16 v[70:73], v[146:149], v[234:237], 0
	v_mfma_f32_16x16x32_bf16 v[66:69], v[154:157], v[234:237], 0
	v_mfma_f32_16x16x32_bf16 v[118:121], v[150:153], v[188:191], v[118:121]
	v_mfma_f32_16x16x32_bf16 v[114:117], v[158:161], v[188:191], v[114:117]
	v_mfma_f32_16x16x32_bf16 v[102:105], v[150:153], v[222:225], v[102:105]
	v_mfma_f32_16x16x32_bf16 v[98:101], v[158:161], v[222:225], v[98:101]
	v_mfma_f32_16x16x32_bf16 v[86:89], v[150:153], v[230:233], v[86:89]
	v_mfma_f32_16x16x32_bf16 v[82:85], v[158:161], v[230:233], v[82:85]
	v_mfma_f32_16x16x32_bf16 v[70:73], v[150:153], v[238:241], v[70:73]
	v_mfma_f32_16x16x32_bf16 v[66:69], v[158:161], v[238:241], v[66:69]
	s_setprio 0
	s_barrier
	s_add_i32 s56, s56, s36
	v_lshl_add_u64 v[242:243], s[24:25], 0, v[162:163]
	s_mov_b32 m0, s56
	ds_read_b128 v[184:187], v217 offset:16384
	ds_read_b128 v[188:191], v217 offset:17408
	ds_read_b128 v[218:221], v217 offset:18432
	ds_read_b128 v[222:225], v217 offset:19456
	ds_read_b128 v[226:229], v217 offset:20480
	ds_read_b128 v[230:233], v217 offset:21504
	ds_read_b128 v[234:237], v217 offset:22528
	ds_read_b128 v[238:241], v217 offset:23552
	global_load_lds_dwordx4 v[242:243], off
	s_add_i32 m0, s56, 0x2000
	s_add_u32 s56, s24, 0x4000
	v_lshl_add_u64 v[242:243], s[24:25], 0, v[178:179]
	s_addc_u32 s57, s25, 0
	s_add_i32 s58, s58, s36
	global_load_lds_dwordx4 v[242:243], off
	v_lshl_add_u64 v[242:243], s[56:57], 0, v[162:163]
	s_mov_b32 m0, s58
	s_nop 0
	global_load_lds_dwordx4 v[242:243], off
	v_lshl_add_u64 v[242:243], s[56:57], 0, v[178:179]
	s_add_i32 m0, s58, 0x2000
	s_nop 0
	global_load_lds_dwordx4 v[242:243], off
	v_lshl_add_u64 v[242:243], s[26:27], 0, v[174:175]
	s_mov_b32 m0, s37
	s_nop 0
	global_load_lds_dwordx4 v[242:243], off
	v_lshl_add_u64 v[242:243], s[26:27], 0, v[176:177]
	s_mov_b32 m0, s38
	s_nop 0
	global_load_lds_dwordx4 v[242:243], off
	s_waitcnt vmcnt(8)
	s_waitcnt lgkmcnt(0)
	s_barrier
; #define PG8_STAGE(bufoff, gbase, voff) do { _Pragma("unroll") for (int _i = 0; _i < 2; ++_i) \
;         __builtin_amdgcn_global_load_lds((const unsigned*)((const char*)(gbase) + (voff)[_i]), (PG8_LAS unsigned*)(lds + (bufoff) + ldsw + _i * 8192), 16, 0, 0); } while (0)
; #define PG8_LDA(dst, b, h) do { _Pragma("unroll") for (int m = 0; m < 4; ++m) _Pragma("unroll") for (int k = 0; k < 2; ++k) dst[m][k] = *(const PG8_LAS frag_t*)(lds + PG8_SA(b, h) + aoff + m * 2048 + k * 1024); } while (0)
; #define PG8_LDB(dst, b, h) do { _Pragma("unroll") for (int n = 0; n < 2; ++n) _Pragma("unroll") for (int k = 0; k < 2; ++k) dst[n][k] = *(const PG8_LAS frag_t*)(lds + PG8_SB(b, h) + boff + n * 2048 + k * 1024); } while (0)
; #define PG8_MMA(ai, bj, At, Bt) do { __builtin_amdgcn_s_setprio(1); _Pragma("unroll") for (int m = 0; m < 4; ++m) _Pragma("unroll") for (int n = 0; n < 2; ++n) _Pragma("unroll") for (int k = 0; k < 2; ++k) \
;         acc[ai][bj][m][n] = mma1v<MMAV>(Bt[n][k], At[m][k], acc[ai][bj][m][n]); __builtin_amdgcn_s_setprio(0); } while (0)
; #define PG8_WAIT_V(n) asm volatile("s_waitcnt vmcnt(" #n ")" ::: "memory")
; #define PG8_WAIT_L(n) asm volatile("s_waitcnt lgkmcnt(" #n ")" ::: "memory")
; #define PG8_BAR __builtin_amdgcn_s_barrier()
; #define PG8_SCHED __builtin_amdgcn_sched_barrier(0)
;     ...
;             PG8_WAIT_V(8); PG8_WAIT_L(0); PG8_BAR; PG8_MMA(1, 0, At, B0); PG8_MMA(1, 1, At, B1); PG8_BAR; PG8_SCHED;
;             PG8_LDB(B0, 1, 0); PG8_LDB(B1, 1, 1); PG8_SCHED; PG8_LDA(At, 1, 0); PG8_STAGE(PG8_SA(0, 1), a2 + hstep, voffA);
;             PG8_WAIT_V(8); PG8_WAIT_L(0); PG8_BAR; PG8_MMA(0, 0, At, B0); PG8_MMA(0, 1, At, B1); PG8_BAR; PG8_SCHED;
	s_setprio 1
	s_waitcnt lgkmcnt(0)
	v_mfma_f32_16x16x32_bf16 v[62:65], v[130:133], v[184:187], 0
	v_mfma_f32_16x16x32_bf16 v[58:61], v[138:141], v[184:187], 0
	v_mfma_f32_16x16x32_bf16 v[46:49], v[130:133], v[218:221], 0
	v_mfma_f32_16x16x32_bf16 v[42:45], v[138:141], v[218:221], 0
	v_mfma_f32_16x16x32_bf16 v[30:33], v[130:133], v[226:229], 0
	v_mfma_f32_16x16x32_bf16 v[26:29], v[138:141], v[226:229], 0
	v_mfma_f32_16x16x32_bf16 v[14:17], v[130:133], v[234:237], 0
	v_mfma_f32_16x16x32_bf16 v[10:13], v[138:141], v[234:237], 0
	v_mfma_f32_16x16x32_bf16 v[62:65], v[134:137], v[188:191], v[62:65]
	v_mfma_f32_16x16x32_bf16 v[58:61], v[142:145], v[188:191], v[58:61]
	v_mfma_f32_16x16x32_bf16 v[46:49], v[134:137], v[222:225], v[46:49]
	v_mfma_f32_16x16x32_bf16 v[42:45], v[142:145], v[222:225], v[42:45]
	v_mfma_f32_16x16x32_bf16 v[30:33], v[134:137], v[230:233], v[30:33]
	v_mfma_f32_16x16x32_bf16 v[26:29], v[142:145], v[230:233], v[26:29]
	v_mfma_f32_16x16x32_bf16 v[14:17], v[134:137], v[238:241], v[14:17]
	v_mfma_f32_16x16x32_bf16 v[10:13], v[142:145], v[238:241], v[10:13]
	s_setprio 0
	s_setprio 1
	v_mfma_f32_16x16x32_bf16 v[54:57], v[146:149], v[184:187], 0
	v_mfma_f32_16x16x32_bf16 v[50:53], v[154:157], v[184:187], 0
	v_mfma_f32_16x16x32_bf16 v[38:41], v[146:149], v[218:221], 0
	v_mfma_f32_16x16x32_bf16 v[34:37], v[154:157], v[218:221], 0
	v_mfma_f32_16x16x32_bf16 v[22:25], v[146:149], v[226:229], 0
	v_mfma_f32_16x16x32_bf16 v[18:21], v[154:157], v[226:229], 0
	v_mfma_f32_16x16x32_bf16 v[6:9], v[146:149], v[234:237], 0
	v_mfma_f32_16x16x32_bf16 v[2:5], v[154:157], v[234:237], 0
	v_mfma_f32_16x16x32_bf16 v[54:57], v[150:153], v[188:191], v[54:57]
	v_mfma_f32_16x16x32_bf16 v[50:53], v[158:161], v[188:191], v[50:53]
	v_mfma_f32_16x16x32_bf16 v[38:41], v[150:153], v[222:225], v[38:41]
	v_mfma_f32_16x16x32_bf16 v[34:37], v[158:161], v[222:225], v[34:37]
	v_mfma_f32_16x16x32_bf16 v[22:25], v[150:153], v[230:233], v[22:25]
	v_mfma_f32_16x16x32_bf16 v[18:21], v[158:161], v[230:233], v[18:21]
	v_mfma_f32_16x16x32_bf16 v[6:9], v[150:153], v[238:241], v[6:9]
	v_mfma_f32_16x16x32_bf16 v[2:5], v[158:161], v[238:241], v[2:5]
	s_setprio 0
	s_barrier
	s_add_i32 s56, 0, 0x18000
	s_add_i32 s57, 0, 0x1c000
	v_add_u32_e32 v142, s56, v216
	v_add_u32_e32 v158, s57, v216
	ds_read_b128 v[130:133], v142
	ds_read_b128 v[134:137], v142 offset:1024
	ds_read_b128 v[138:141], v142 offset:2048
	ds_read_b128 v[142:145], v142 offset:3072
	ds_read_b128 v[146:149], v158
	ds_read_b128 v[150:153], v158 offset:1024
	ds_read_b128 v[154:157], v158 offset:2048
	ds_read_b128 v[158:161], v158 offset:3072
	s_add_u32 s26, s26, 0x4000
	s_addc_u32 s27, s27, 0
	s_mov_b32 m0, s39
	v_lshl_add_u64 v[242:243], s[26:27], 0, v[174:175]
	ds_read_b128 v[184:187], v217 offset:32768
	ds_read_b128 v[188:191], v217 offset:33792
	ds_read_b128 v[218:221], v217 offset:34816
	ds_read_b128 v[222:225], v217 offset:35840
	ds_read_b128 v[226:229], v217 offset:36864
	ds_read_b128 v[230:233], v217 offset:37888
	ds_read_b128 v[234:237], v217 offset:38912
	ds_read_b128 v[238:241], v217 offset:39936
	global_load_lds_dwordx4 v[242:243], off
	v_lshl_add_u64 v[242:243], s[26:27], 0, v[176:177]
	s_mov_b32 m0, s40
	s_nop 0
	global_load_lds_dwordx4 v[242:243], off
	s_waitcnt vmcnt(8)
	s_waitcnt lgkmcnt(0)
	s_barrier
	s_setprio 1
	s_waitcnt lgkmcnt(0)
	v_mfma_f32_16x16x32_bf16 v[126:129], v[130:133], v[184:187], v[126:129]
	v_mfma_f32_16x16x32_bf16 v[122:125], v[138:141], v[184:187], v[122:125]
	v_mfma_f32_16x16x32_bf16 v[110:113], v[130:133], v[218:221], v[110:113]
	v_mfma_f32_16x16x32_bf16 v[106:109], v[138:141], v[218:221], v[106:109]
	v_mfma_f32_16x16x32_bf16 v[94:97], v[130:133], v[226:229], v[94:97]
	v_mfma_f32_16x16x32_bf16 v[90:93], v[138:141], v[226:229], v[90:93]
	v_mfma_f32_16x16x32_bf16 v[78:81], v[130:133], v[234:237], v[78:81]
	v_mfma_f32_16x16x32_bf16 v[74:77], v[138:141], v[234:237], v[74:77]
	v_mfma_f32_16x16x32_bf16 v[126:129], v[134:137], v[188:191], v[126:129]
	v_mfma_f32_16x16x32_bf16 v[122:125], v[142:145], v[188:191], v[122:125]
	v_mfma_f32_16x16x32_bf16 v[110:113], v[134:137], v[222:225], v[110:113]
	v_mfma_f32_16x16x32_bf16 v[106:109], v[142:145], v[222:225], v[106:109]
	v_mfma_f32_16x16x32_bf16 v[94:97], v[134:137], v[230:233], v[94:97]
	v_mfma_f32_16x16x32_bf16 v[90:93], v[142:145], v[230:233], v[90:93]
	v_mfma_f32_16x16x32_bf16 v[78:81], v[134:137], v[238:241], v[78:81]
	v_mfma_f32_16x16x32_bf16 v[74:77], v[142:145], v[238:241], v[74:77]
	s_setprio 0
	s_setprio 1
	v_mfma_f32_16x16x32_bf16 v[118:121], v[146:149], v[184:187], v[118:121]
	v_mfma_f32_16x16x32_bf16 v[114:117], v[154:157], v[184:187], v[114:117]
	v_mfma_f32_16x16x32_bf16 v[102:105], v[146:149], v[218:221], v[102:105]
	v_mfma_f32_16x16x32_bf16 v[98:101], v[154:157], v[218:221], v[98:101]
	v_mfma_f32_16x16x32_bf16 v[86:89], v[146:149], v[226:229], v[86:89]
	v_mfma_f32_16x16x32_bf16 v[82:85], v[154:157], v[226:229], v[82:85]
	v_mfma_f32_16x16x32_bf16 v[70:73], v[146:149], v[234:237], v[70:73]
	v_mfma_f32_16x16x32_bf16 v[66:69], v[154:157], v[234:237], v[66:69]
	v_mfma_f32_16x16x32_bf16 v[118:121], v[150:153], v[188:191], v[118:121]
	v_mfma_f32_16x16x32_bf16 v[114:117], v[158:161], v[188:191], v[114:117]
	v_mfma_f32_16x16x32_bf16 v[102:105], v[150:153], v[222:225], v[102:105]
	v_mfma_f32_16x16x32_bf16 v[98:101], v[158:161], v[222:225], v[98:101]
	v_mfma_f32_16x16x32_bf16 v[86:89], v[150:153], v[230:233], v[86:89]
	v_mfma_f32_16x16x32_bf16 v[82:85], v[158:161], v[230:233], v[82:85]
	v_mfma_f32_16x16x32_bf16 v[70:73], v[150:153], v[238:241], v[70:73]
	v_mfma_f32_16x16x32_bf16 v[66:69], v[158:161], v[238:241], v[66:69]
	s_setprio 0
	s_barrier
; #define PG8_STAGE(bufoff, gbase, voff) do { _Pragma("unroll") for (int _i = 0; _i < 2; ++_i) \
;         __builtin_amdgcn_global_load_lds((const unsigned*)((const char*)(gbase) + (voff)[_i]), (PG8_LAS unsigned*)(lds + (bufoff) + ldsw + _i * 8192), 16, 0, 0); } while (0)
; #define PG8_LDA(dst, b, h) do { _Pragma("unroll") for (int m = 0; m < 4; ++m) _Pragma("unroll") for (int k = 0; k < 2; ++k) dst[m][k] = *(const PG8_LAS frag_t*)(lds + PG8_SA(b, h) + aoff + m * 2048 + k * 1024); } while (0)
; #define PG8_MMA(ai, bj, At, Bt) do { __builtin_amdgcn_s_setprio(1); _Pragma("unroll") for (int m = 0; m < 4; ++m) _Pragma("unroll") for (int n = 0; n < 2; ++n) _Pragma("unroll") for (int k = 0; k < 2; ++k) \
;         acc[ai][bj][m][n] = mma1v<MMAV>(Bt[n][k], At[m][k], acc[ai][bj][m][n]); __builtin_amdgcn_s_setprio(0); } while (0)
; #define PG8_WAIT_V(n) asm volatile("s_waitcnt vmcnt(" #n ")" ::: "memory")
; #define PG8_WAIT_L(n) asm volatile("s_waitcnt lgkmcnt(" #n ")" ::: "memory")
; #define PG8_BAR __builtin_amdgcn_s_barrier()
; #define PG8_SCHED __builtin_amdgcn_sched_barrier(0)
;     ...
;         for (int t = 0; t < nt; t += 2) {
;     ...
;             PG8_LDA(At, 1, 1); PG8_STAGE(PG8_SB(1, 0), b3, voffB); PG8_STAGE(PG8_SB(1, 1), b3 + hstepB, voffB); PG8_STAGE(PG8_SA(1, 0), a3, voffA);
;             PG8_WAIT_V(8); PG8_WAIT_L(0); PG8_BAR; PG8_MMA(1, 0, At, B0); PG8_MMA(1, 1, At, B1); PG8_BAR; PG8_SCHED;
	s_add_u32 s26, s24, 0x8000
	s_addc_u32 s27, s25, 0
	s_add_i32 s56, s56, s36
	v_lshl_add_u64 v[242:243], s[26:27], 0, v[162:163]
	s_mov_b32 m0, s56
	ds_read_b128 v[184:187], v217 offset:49152
	ds_read_b128 v[188:191], v217 offset:50176
	ds_read_b128 v[218:221], v217 offset:51200
	ds_read_b128 v[222:225], v217 offset:52224
	ds_read_b128 v[226:229], v217 offset:53248
	ds_read_b128 v[230:233], v217 offset:54272
	ds_read_b128 v[234:237], v217 offset:55296
	ds_read_b128 v[238:241], v217 offset:56320
	global_load_lds_dwordx4 v[242:243], off
	s_add_i32 m0, s56, 0x2000
	s_add_u32 s24, s24, 0xc000
	v_lshl_add_u64 v[242:243], s[26:27], 0, v[178:179]
	s_addc_u32 s25, s25, 0
	s_add_i32 s26, s57, s36
	global_load_lds_dwordx4 v[242:243], off
	v_lshl_add_u64 v[242:243], s[24:25], 0, v[162:163]
	s_mov_b32 m0, s26
	s_nop 0
	global_load_lds_dwordx4 v[242:243], off
	v_lshl_add_u64 v[242:243], s[24:25], 0, v[178:179]
	s_add_i32 m0, s26, 0x2000
	s_nop 0
	global_load_lds_dwordx4 v[242:243], off
	v_lshl_add_u64 v[242:243], s[8:9], 0, v[174:175]
	s_mov_b32 m0, s44
	s_nop 0
	global_load_lds_dwordx4 v[242:243], off
	v_lshl_add_u64 v[242:243], s[8:9], 0, v[176:177]
	s_mov_b32 m0, s45
	s_nop 0
	global_load_lds_dwordx4 v[242:243], off
	s_waitcnt vmcnt(8)
	s_waitcnt lgkmcnt(0)
	s_barrier
	s_setprio 1
	s_waitcnt lgkmcnt(0)
	v_mfma_f32_16x16x32_bf16 v[62:65], v[130:133], v[184:187], v[62:65]
	v_mfma_f32_16x16x32_bf16 v[58:61], v[138:141], v[184:187], v[58:61]
	v_mfma_f32_16x16x32_bf16 v[46:49], v[130:133], v[218:221], v[46:49]
	v_mfma_f32_16x16x32_bf16 v[42:45], v[138:141], v[218:221], v[42:45]
	v_mfma_f32_16x16x32_bf16 v[30:33], v[130:133], v[226:229], v[30:33]
	v_mfma_f32_16x16x32_bf16 v[26:29], v[138:141], v[226:229], v[26:29]
	v_mfma_f32_16x16x32_bf16 v[14:17], v[130:133], v[234:237], v[14:17]
	v_mfma_f32_16x16x32_bf16 v[10:13], v[138:141], v[234:237], v[10:13]
	v_mfma_f32_16x16x32_bf16 v[62:65], v[134:137], v[188:191], v[62:65]
	v_mfma_f32_16x16x32_bf16 v[58:61], v[142:145], v[188:191], v[58:61]
	v_mfma_f32_16x16x32_bf16 v[46:49], v[134:137], v[222:225], v[46:49]
	v_mfma_f32_16x16x32_bf16 v[42:45], v[142:145], v[222:225], v[42:45]
	v_mfma_f32_16x16x32_bf16 v[30:33], v[134:137], v[230:233], v[30:33]
	v_mfma_f32_16x16x32_bf16 v[26:29], v[142:145], v[230:233], v[26:29]
	v_mfma_f32_16x16x32_bf16 v[14:17], v[134:137], v[238:241], v[14:17]
	v_mfma_f32_16x16x32_bf16 v[10:13], v[142:145], v[238:241], v[10:13]
	s_setprio 0
	s_setprio 1
	v_mfma_f32_16x16x32_bf16 v[54:57], v[146:149], v[184:187], v[54:57]
	v_mfma_f32_16x16x32_bf16 v[50:53], v[154:157], v[184:187], v[50:53]
	v_mfma_f32_16x16x32_bf16 v[38:41], v[146:149], v[218:221], v[38:41]
	v_mfma_f32_16x16x32_bf16 v[34:37], v[154:157], v[218:221], v[34:37]
	v_mfma_f32_16x16x32_bf16 v[22:25], v[146:149], v[226:229], v[22:25]
	v_mfma_f32_16x16x32_bf16 v[18:21], v[154:157], v[226:229], v[18:21]
	v_mfma_f32_16x16x32_bf16 v[6:9], v[146:149], v[234:237], v[6:9]
	v_mfma_f32_16x16x32_bf16 v[2:5], v[154:157], v[234:237], v[2:5]
	v_mfma_f32_16x16x32_bf16 v[54:57], v[150:153], v[188:191], v[54:57]
	v_mfma_f32_16x16x32_bf16 v[50:53], v[158:161], v[188:191], v[50:53]
	v_mfma_f32_16x16x32_bf16 v[38:41], v[150:153], v[222:225], v[38:41]
	v_mfma_f32_16x16x32_bf16 v[34:37], v[158:161], v[222:225], v[34:37]
	v_mfma_f32_16x16x32_bf16 v[22:25], v[150:153], v[230:233], v[22:25]
	v_mfma_f32_16x16x32_bf16 v[18:21], v[158:161], v[230:233], v[18:21]
	v_mfma_f32_16x16x32_bf16 v[6:9], v[150:153], v[238:241], v[6:9]
	v_mfma_f32_16x16x32_bf16 v[2:5], v[158:161], v[238:241], v[2:5]
	s_setprio 0
	s_barrier
	s_add_i32 s55, s55, 2
	s_add_u32 s6, s6, 0x10000
	s_addc_u32 s7, s7, 0
	s_add_u32 s53, s53, 0x10000
	s_addc_u32 s54, s54, 0
	.p2align	6

; #define PG8_STAGE(bufoff, gbase, voff) do { _Pragma("unroll") for (int _i = 0; _i < 2; ++_i) \
;         __builtin_amdgcn_global_load_lds((const unsigned*)((const char*)(gbase) + (voff)[_i]), (PG8_LAS unsigned*)(lds + (bufoff) + ldsw + _i * 8192), 16, 0, 0); } while (0)
; #define PG8_LDA(dst, b, h) do { _Pragma("unroll") for (int m = 0; m < 4; ++m) _Pragma("unroll") for (int k = 0; k < 2; ++k) dst[m][k] = *(const PG8_LAS frag_t*)(lds + PG8_SA(b, h) + aoff + m * 2048 + k * 1024); } while (0)
; #define PG8_LDB(dst, b, h) do { _Pragma("unroll") for (int n = 0; n < 2; ++n) _Pragma("unroll") for (int k = 0; k < 2; ++k) dst[n][k] = *(const PG8_LAS frag_t*)(lds + PG8_SB(b, h) + boff + n * 2048 + k * 1024); } while (0)
; #define PG8_MMA(ai, bj, At, Bt) do { __builtin_amdgcn_s_setprio(1); _Pragma("unroll") for (int m = 0; m < 4; ++m) _Pragma("unroll") for (int n = 0; n < 2; ++n) _Pragma("unroll") for (int k = 0; k < 2; ++k) \
;         acc[ai][bj][m][n] = mma1v<MMAV>(Bt[n][k], At[m][k], acc[ai][bj][m][n]); __builtin_amdgcn_s_setprio(0); } while (0)
; #define PG8_WAIT_V(n) asm volatile("s_waitcnt vmcnt(" #n ")" ::: "memory")
; #define PG8_WAIT_L(n) asm volatile("s_waitcnt lgkmcnt(" #n ")" ::: "memory")
; #define PG8_BAR __builtin_amdgcn_s_barrier()
;     ...
;         const char* nA = has_next ? (const char*)g.A + (size_t)nxt.pm * tstep : cA; const char* nB = has_next ? (const char*)g.Bt + (size_t)nxt.pn * tstep : cB;
;         for (int t = 0; t < nt; t += 2) {
;             const bool last = (t == nt - 2);
;             const char* a1 = cA + (size_t)(t + 1) * kstep;
;             const char* a2 = last ? nA : cA + (size_t)(t + 2) * kstep; const char* b2 = last ? nB : cB + (size_t)(t + 2) * kstepB;
;             const char* a3 = a2 + kstep; const char* b3 = b2 + kstepB;
;             if (last && has_next) S.a_ready(nxt);
;             if constexpr (SP2) {
;             PG8_LDB(B0, 0, 0); PG8_LDB(B1, 0, 1); PG8_SCHED; PG8_LDA(At, 0, 0); PG8_STAGE(PG8_SA(1, 1), a1 + hstep, voffA);
;             PG8_WAIT_V(8); PG8_WAIT_L(0); PG8_BAR; PG8_MMA(0, 0, At, B0); PG8_MMA(0, 1, At, B1); PG8_BAR; PG8_SCHED;
;             PG8_LDA(At, 0, 1); PG8_STAGE(PG8_SB(0, 0), b2, voffB); PG8_STAGE(PG8_SB(0, 1), b2 + hstepB, voffB); PG8_STAGE(PG8_SA(0, 0), a2, voffA);
;             PG8_WAIT_V(8); PG8_WAIT_L(0); PG8_BAR; PG8_MMA(1, 0, At, B0); PG8_MMA(1, 1, At, B1); PG8_BAR; PG8_SCHED;
.LBB0_368:
	s_ashr_i32 s31, s30, 31
	s_lshl_b64 s[10:11], s[30:31], 20
	s_add_u32 s34, s48, s10
	s_addc_u32 s35, s49, s11
	s_and_b64 s[10:11], s[6:7], exec
	s_cselect_b32 s31, s35, s9
	s_cselect_b32 s39, s34, s8
	s_ashr_i32 s29, s28, 31
	s_lshl_b64 s[10:11], s[28:29], 20
	s_add_u32 s36, s50, s10
	s_addc_u32 s37, s51, s11
	s_and_b64 s[10:11], s[6:7], exec
	s_cselect_b32 s29, s37, s1
	s_cselect_b32 s40, s36, s0
	s_add_u32 s41, s0, 0x10000
	s_addc_u32 s42, s1, 0
	s_add_u32 s0, s8, 0x80080
	s_addc_u32 s1, s9, 0
	s_mov_b32 s43, -2
	s_add_u32 s8, s0, 0xfff80080
	s_addc_u32 s9, s1, -1
	s_add_i32 s80, 0, 0x10000
	s_cmp_eq_u32 s43, 28
	s_cselect_b32 s11, s31, s9
	s_cselect_b32 s10, s39, s8
	s_cselect_b32 s9, s29, s42
	s_cselect_b32 s8, s40, s41
	s_add_i32 s82, 0, 0x14000
	v_add_u32_e32 v154, s80, v161
	v_add_u32_e32 v158, s82, v161
	ds_read_b128 v[130:133], v154
	ds_read_b128 v[134:137], v154 offset:1024
	ds_read_b128 v[138:141], v154 offset:2048
	ds_read_b128 v[154:157], v154 offset:3072
	ds_read_b128 v[176:179], v158
	ds_read_b128 v[180:183], v158 offset:1024
	ds_read_b128 v[184:187], v158 offset:2048
	ds_read_b128 v[188:191], v158 offset:3072
	v_lshl_add_u64 v[248:249], s[0:1], 0, v[150:151]
	s_add_i32 m0, s21, 0xc000
	ds_read_b128 v[216:219], v175
	ds_read_b128 v[220:223], v175 offset:1024
	ds_read_b128 v[224:227], v175 offset:2048
	ds_read_b128 v[228:231], v175 offset:3072
	ds_read_b128 v[232:235], v175 offset:4096
	ds_read_b128 v[236:239], v175 offset:5120
	ds_read_b128 v[240:243], v175 offset:6144
	ds_read_b128 v[244:247], v175 offset:7168
	global_load_lds_dwordx4 v[248:249], off
	v_lshl_add_u64 v[248:249], s[0:1], 0, v[152:153]
	s_add_i32 m0, s21, 0xe000
	s_nop 0
	global_load_lds_dwordx4 v[248:249], off
	s_waitcnt vmcnt(24)
	s_waitcnt lgkmcnt(0)
	s_barrier
	s_setprio 1
	s_waitcnt lgkmcnt(0)
	v_mfma_f32_16x16x32_bf16 v[126:129], v[130:133], v[216:219], 0
	v_mfma_f32_16x16x32_bf16 v[122:125], v[138:141], v[216:219], 0
	v_mfma_f32_16x16x32_bf16 v[110:113], v[130:133], v[224:227], 0
	v_mfma_f32_16x16x32_bf16 v[106:109], v[138:141], v[224:227], 0
	v_mfma_f32_16x16x32_bf16 v[94:97], v[130:133], v[232:235], 0
	v_mfma_f32_16x16x32_bf16 v[90:93], v[138:141], v[232:235], 0
	v_mfma_f32_16x16x32_bf16 v[78:81], v[130:133], v[240:243], 0
	v_mfma_f32_16x16x32_bf16 v[74:77], v[138:141], v[240:243], 0
	v_mfma_f32_16x16x32_bf16 v[126:129], v[134:137], v[220:223], v[126:129]
	v_mfma_f32_16x16x32_bf16 v[122:125], v[154:157], v[220:223], v[122:125]
	v_mfma_f32_16x16x32_bf16 v[110:113], v[134:137], v[228:231], v[110:113]
	v_mfma_f32_16x16x32_bf16 v[106:109], v[154:157], v[228:231], v[106:109]
	v_mfma_f32_16x16x32_bf16 v[94:97], v[134:137], v[236:239], v[94:97]
	v_mfma_f32_16x16x32_bf16 v[90:93], v[154:157], v[236:239], v[90:93]
	v_mfma_f32_16x16x32_bf16 v[78:81], v[134:137], v[244:247], v[78:81]
	v_mfma_f32_16x16x32_bf16 v[74:77], v[154:157], v[244:247], v[74:77]
	s_setprio 0
	s_setprio 1
	v_mfma_f32_16x16x32_bf16 v[118:121], v[176:179], v[216:219], 0
	v_mfma_f32_16x16x32_bf16 v[114:117], v[184:187], v[216:219], 0
	v_mfma_f32_16x16x32_bf16 v[102:105], v[176:179], v[224:227], 0
	v_mfma_f32_16x16x32_bf16 v[98:101], v[184:187], v[224:227], 0
	v_mfma_f32_16x16x32_bf16 v[86:89], v[176:179], v[232:235], 0
	v_mfma_f32_16x16x32_bf16 v[82:85], v[184:187], v[232:235], 0
	v_mfma_f32_16x16x32_bf16 v[70:73], v[176:179], v[240:243], 0
	v_mfma_f32_16x16x32_bf16 v[66:69], v[184:187], v[240:243], 0
	v_mfma_f32_16x16x32_bf16 v[118:121], v[180:183], v[220:223], v[118:121]
	v_mfma_f32_16x16x32_bf16 v[114:117], v[188:191], v[220:223], v[114:117]
	v_mfma_f32_16x16x32_bf16 v[102:105], v[180:183], v[228:231], v[102:105]
	v_mfma_f32_16x16x32_bf16 v[98:101], v[188:191], v[228:231], v[98:101]
	v_mfma_f32_16x16x32_bf16 v[86:89], v[180:183], v[236:239], v[86:89]
	v_mfma_f32_16x16x32_bf16 v[82:85], v[188:191], v[236:239], v[82:85]
	v_mfma_f32_16x16x32_bf16 v[70:73], v[180:183], v[244:247], v[70:73]
	v_mfma_f32_16x16x32_bf16 v[66:69], v[188:191], v[244:247], v[66:69]
	s_setprio 0
	s_barrier
	s_add_i32 s80, s80, s53
	v_lshl_add_u64 v[248:249], s[8:9], 0, v[142:143]
	s_mov_b32 m0, s80
	ds_read_b128 v[216:219], v175 offset:16384
	ds_read_b128 v[220:223], v175 offset:17408
	ds_read_b128 v[224:227], v175 offset:18432
	ds_read_b128 v[228:231], v175 offset:19456
	ds_read_b128 v[232:235], v175 offset:20480
	ds_read_b128 v[236:239], v175 offset:21504
	ds_read_b128 v[240:243], v175 offset:22528
	ds_read_b128 v[244:247], v175 offset:23552
	global_load_lds_dwordx4 v[248:249], off
	s_add_i32 m0, s80, 0x2000
	s_add_u32 s80, s8, 0x4000
	v_lshl_add_u64 v[248:249], s[8:9], 0, v[146:147]
	s_addc_u32 s81, s9, 0
	s_add_i32 s82, s82, s53
	global_load_lds_dwordx4 v[248:249], off
	v_lshl_add_u64 v[248:249], s[80:81], 0, v[142:143]
	s_mov_b32 m0, s82
	v_lshl_add_u64 v[250:251], s[10:11], 0, v[144:145]
	global_load_lds_dwordx4 v[248:249], off
	v_lshl_add_u64 v[248:249], s[80:81], 0, v[146:147]
	s_add_i32 m0, s82, 0x2000
	s_nop 0
	global_load_lds_dwordx4 v[248:249], off
	v_lshl_add_u64 v[248:249], s[10:11], 0, v[162:163]
	s_mov_b32 m0, s21
	s_nop 0
	global_load_lds_dwordx4 v[248:249], off
	s_mov_b32 m0, s54
	s_nop 0
	global_load_lds_dwordx4 v[250:251], off
	s_waitcnt vmcnt(8)
	s_waitcnt lgkmcnt(0)
	s_barrier
; #define PG8_STAGE(bufoff, gbase, voff) do { _Pragma("unroll") for (int _i = 0; _i < 2; ++_i) \
;         __builtin_amdgcn_global_load_lds((const unsigned*)((const char*)(gbase) + (voff)[_i]), (PG8_LAS unsigned*)(lds + (bufoff) + ldsw + _i * 8192), 16, 0, 0); } while (0)
; #define PG8_LDA(dst, b, h) do { _Pragma("unroll") for (int m = 0; m < 4; ++m) _Pragma("unroll") for (int k = 0; k < 2; ++k) dst[m][k] = *(const PG8_LAS frag_t*)(lds + PG8_SA(b, h) + aoff + m * 2048 + k * 1024); } while (0)
; #define PG8_LDB(dst, b, h) do { _Pragma("unroll") for (int n = 0; n < 2; ++n) _Pragma("unroll") for (int k = 0; k < 2; ++k) dst[n][k] = *(const PG8_LAS frag_t*)(lds + PG8_SB(b, h) + boff + n * 2048 + k * 1024); } while (0)
; #define PG8_MMA(ai, bj, At, Bt) do { __builtin_amdgcn_s_setprio(1); _Pragma("unroll") for (int m = 0; m < 4; ++m) _Pragma("unroll") for (int n = 0; n < 2; ++n) _Pragma("unroll") for (int k = 0; k < 2; ++k) \
;         acc[ai][bj][m][n] = mma1v<MMAV>(Bt[n][k], At[m][k], acc[ai][bj][m][n]); __builtin_amdgcn_s_setprio(0); } while (0)
; #define PG8_WAIT_V(n) asm volatile("s_waitcnt vmcnt(" #n ")" ::: "memory")
; #define PG8_WAIT_L(n) asm volatile("s_waitcnt lgkmcnt(" #n ")" ::: "memory")
; #define PG8_BAR __builtin_amdgcn_s_barrier()
; #define PG8_SCHED __builtin_amdgcn_sched_barrier(0)
;     ...
;             PG8_WAIT_V(8); PG8_WAIT_L(0); PG8_BAR; PG8_MMA(1, 0, At, B0); PG8_MMA(1, 1, At, B1); PG8_BAR; PG8_SCHED;
;             PG8_LDB(B0, 1, 0); PG8_LDB(B1, 1, 1); PG8_SCHED; PG8_LDA(At, 1, 0); PG8_STAGE(PG8_SA(0, 1), a2 + hstep, voffA);
;             PG8_WAIT_V(8); PG8_WAIT_L(0); PG8_BAR; PG8_MMA(0, 0, At, B0); PG8_MMA(0, 1, At, B1); PG8_BAR; PG8_SCHED;
	s_setprio 1
	s_waitcnt lgkmcnt(0)
	v_mfma_f32_16x16x32_bf16 v[62:65], v[130:133], v[216:219], 0
	v_mfma_f32_16x16x32_bf16 v[58:61], v[138:141], v[216:219], 0
	v_mfma_f32_16x16x32_bf16 v[46:49], v[130:133], v[224:227], 0
	v_mfma_f32_16x16x32_bf16 v[42:45], v[138:141], v[224:227], 0
	v_mfma_f32_16x16x32_bf16 v[30:33], v[130:133], v[232:235], 0
	v_mfma_f32_16x16x32_bf16 v[26:29], v[138:141], v[232:235], 0
	v_mfma_f32_16x16x32_bf16 v[14:17], v[130:133], v[240:243], 0
	v_mfma_f32_16x16x32_bf16 v[10:13], v[138:141], v[240:243], 0
	v_mfma_f32_16x16x32_bf16 v[62:65], v[134:137], v[220:223], v[62:65]
	v_mfma_f32_16x16x32_bf16 v[58:61], v[154:157], v[220:223], v[58:61]
	v_mfma_f32_16x16x32_bf16 v[46:49], v[134:137], v[228:231], v[46:49]
	v_mfma_f32_16x16x32_bf16 v[42:45], v[154:157], v[228:231], v[42:45]
	v_mfma_f32_16x16x32_bf16 v[30:33], v[134:137], v[236:239], v[30:33]
	v_mfma_f32_16x16x32_bf16 v[26:29], v[154:157], v[236:239], v[26:29]
	v_mfma_f32_16x16x32_bf16 v[14:17], v[134:137], v[244:247], v[14:17]
	v_mfma_f32_16x16x32_bf16 v[10:13], v[154:157], v[244:247], v[10:13]
	s_setprio 0
	s_setprio 1
	v_mfma_f32_16x16x32_bf16 v[54:57], v[176:179], v[216:219], 0
	v_mfma_f32_16x16x32_bf16 v[50:53], v[184:187], v[216:219], 0
	v_mfma_f32_16x16x32_bf16 v[38:41], v[176:179], v[224:227], 0
	v_mfma_f32_16x16x32_bf16 v[34:37], v[184:187], v[224:227], 0
	v_mfma_f32_16x16x32_bf16 v[22:25], v[176:179], v[232:235], 0
	v_mfma_f32_16x16x32_bf16 v[18:21], v[184:187], v[232:235], 0
	v_mfma_f32_16x16x32_bf16 v[6:9], v[176:179], v[240:243], 0
	v_mfma_f32_16x16x32_bf16 v[2:5], v[184:187], v[240:243], 0
	v_mfma_f32_16x16x32_bf16 v[54:57], v[180:183], v[220:223], v[54:57]
	v_mfma_f32_16x16x32_bf16 v[50:53], v[188:191], v[220:223], v[50:53]
	v_mfma_f32_16x16x32_bf16 v[38:41], v[180:183], v[228:231], v[38:41]
	v_mfma_f32_16x16x32_bf16 v[34:37], v[188:191], v[228:231], v[34:37]
	v_mfma_f32_16x16x32_bf16 v[22:25], v[180:183], v[236:239], v[22:25]
	v_mfma_f32_16x16x32_bf16 v[18:21], v[188:191], v[236:239], v[18:21]
	v_mfma_f32_16x16x32_bf16 v[6:9], v[180:183], v[244:247], v[6:9]
	v_mfma_f32_16x16x32_bf16 v[2:5], v[188:191], v[244:247], v[2:5]
	s_setprio 0
	s_barrier
	s_add_i32 s80, 0, 0x18000
	s_add_i32 s81, 0, 0x1c000
	v_add_u32_e32 v154, s80, v161
	v_add_u32_e32 v158, s81, v161
	ds_read_b128 v[130:133], v154
	ds_read_b128 v[134:137], v154 offset:1024
	ds_read_b128 v[138:141], v154 offset:2048
	ds_read_b128 v[154:157], v154 offset:3072
	ds_read_b128 v[176:179], v158
	ds_read_b128 v[180:183], v158 offset:1024
	ds_read_b128 v[184:187], v158 offset:2048
	ds_read_b128 v[188:191], v158 offset:3072
	s_add_u32 s10, s10, 0x80000
	s_addc_u32 s11, s11, 0
	s_mov_b32 m0, s55
	v_lshl_add_u64 v[252:253], s[10:11], 0, v[162:163]
	ds_read_b128 v[216:219], v175 offset:32768
	ds_read_b128 v[220:223], v175 offset:33792
	ds_read_b128 v[224:227], v175 offset:34816
	ds_read_b128 v[228:231], v175 offset:35840
	ds_read_b128 v[232:235], v175 offset:36864
	ds_read_b128 v[236:239], v175 offset:37888
	ds_read_b128 v[240:243], v175 offset:38912
	ds_read_b128 v[244:247], v175 offset:39936
	global_load_lds_dwordx4 v[252:253], off
	v_lshl_add_u64 v[252:253], s[10:11], 0, v[144:145]
	s_mov_b32 m0, s56
	s_nop 0
	global_load_lds_dwordx4 v[252:253], off
	s_waitcnt vmcnt(8)
	s_waitcnt lgkmcnt(0)
	s_barrier
	s_setprio 1
	s_waitcnt lgkmcnt(0)
	v_mfma_f32_16x16x32_bf16 v[126:129], v[130:133], v[216:219], v[126:129]
	v_mfma_f32_16x16x32_bf16 v[122:125], v[138:141], v[216:219], v[122:125]
	v_mfma_f32_16x16x32_bf16 v[110:113], v[130:133], v[224:227], v[110:113]
	v_mfma_f32_16x16x32_bf16 v[106:109], v[138:141], v[224:227], v[106:109]
	v_mfma_f32_16x16x32_bf16 v[94:97], v[130:133], v[232:235], v[94:97]
	v_mfma_f32_16x16x32_bf16 v[90:93], v[138:141], v[232:235], v[90:93]
	v_mfma_f32_16x16x32_bf16 v[78:81], v[130:133], v[240:243], v[78:81]
	v_mfma_f32_16x16x32_bf16 v[74:77], v[138:141], v[240:243], v[74:77]
	v_mfma_f32_16x16x32_bf16 v[126:129], v[134:137], v[220:223], v[126:129]
	v_mfma_f32_16x16x32_bf16 v[122:125], v[154:157], v[220:223], v[122:125]
	v_mfma_f32_16x16x32_bf16 v[110:113], v[134:137], v[228:231], v[110:113]
	v_mfma_f32_16x16x32_bf16 v[106:109], v[154:157], v[228:231], v[106:109]
	v_mfma_f32_16x16x32_bf16 v[94:97], v[134:137], v[236:239], v[94:97]
	v_mfma_f32_16x16x32_bf16 v[90:93], v[154:157], v[236:239], v[90:93]
	v_mfma_f32_16x16x32_bf16 v[78:81], v[134:137], v[244:247], v[78:81]
	v_mfma_f32_16x16x32_bf16 v[74:77], v[154:157], v[244:247], v[74:77]
	s_setprio 0
	s_setprio 1
	v_mfma_f32_16x16x32_bf16 v[118:121], v[176:179], v[216:219], v[118:121]
	v_mfma_f32_16x16x32_bf16 v[114:117], v[184:187], v[216:219], v[114:117]
	v_mfma_f32_16x16x32_bf16 v[102:105], v[176:179], v[224:227], v[102:105]
	v_mfma_f32_16x16x32_bf16 v[98:101], v[184:187], v[224:227], v[98:101]
	v_mfma_f32_16x16x32_bf16 v[86:89], v[176:179], v[232:235], v[86:89]
	v_mfma_f32_16x16x32_bf16 v[82:85], v[184:187], v[232:235], v[82:85]
	v_mfma_f32_16x16x32_bf16 v[70:73], v[176:179], v[240:243], v[70:73]
	v_mfma_f32_16x16x32_bf16 v[66:69], v[184:187], v[240:243], v[66:69]
	v_mfma_f32_16x16x32_bf16 v[118:121], v[180:183], v[220:223], v[118:121]
	v_mfma_f32_16x16x32_bf16 v[114:117], v[188:191], v[220:223], v[114:117]
	v_mfma_f32_16x16x32_bf16 v[102:105], v[180:183], v[228:231], v[102:105]
	v_mfma_f32_16x16x32_bf16 v[98:101], v[188:191], v[228:231], v[98:101]
	v_mfma_f32_16x16x32_bf16 v[86:89], v[180:183], v[236:239], v[86:89]
	v_mfma_f32_16x16x32_bf16 v[82:85], v[188:191], v[236:239], v[82:85]
	v_mfma_f32_16x16x32_bf16 v[70:73], v[180:183], v[244:247], v[70:73]
	v_mfma_f32_16x16x32_bf16 v[66:69], v[188:191], v[244:247], v[66:69]
	s_setprio 0
	s_barrier
; #define PG8_STAGE(bufoff, gbase, voff) do { _Pragma("unroll") for (int _i = 0; _i < 2; ++_i) \
;         __builtin_amdgcn_global_load_lds((const unsigned*)((const char*)(gbase) + (voff)[_i]), (PG8_LAS unsigned*)(lds + (bufoff) + ldsw + _i * 8192), 16, 0, 0); } while (0)
; #define PG8_LDA(dst, b, h) do { _Pragma("unroll") for (int m = 0; m < 4; ++m) _Pragma("unroll") for (int k = 0; k < 2; ++k) dst[m][k] = *(const PG8_LAS frag_t*)(lds + PG8_SA(b, h) + aoff + m * 2048 + k * 1024); } while (0)
; #define PG8_MMA(ai, bj, At, Bt) do { __builtin_amdgcn_s_setprio(1); _Pragma("unroll") for (int m = 0; m < 4; ++m) _Pragma("unroll") for (int n = 0; n < 2; ++n) _Pragma("unroll") for (int k = 0; k < 2; ++k) \
;         acc[ai][bj][m][n] = mma1v<MMAV>(Bt[n][k], At[m][k], acc[ai][bj][m][n]); __builtin_amdgcn_s_setprio(0); } while (0)
; #define PG8_WAIT_V(n) asm volatile("s_waitcnt vmcnt(" #n ")" ::: "memory")
; #define PG8_WAIT_L(n) asm volatile("s_waitcnt lgkmcnt(" #n ")" ::: "memory")
; #define PG8_BAR __builtin_amdgcn_s_barrier()
; #define PG8_SCHED __builtin_amdgcn_sched_barrier(0)
;     ...
;         for (int t = 0; t < nt; t += 2) {
;     ...
;             PG8_LDA(At, 1, 1); PG8_STAGE(PG8_SB(1, 0), b3, voffB); PG8_STAGE(PG8_SB(1, 1), b3 + hstepB, voffB); PG8_STAGE(PG8_SA(1, 0), a3, voffA);
;             PG8_WAIT_V(8); PG8_WAIT_L(0); PG8_BAR; PG8_MMA(1, 0, At, B0); PG8_MMA(1, 1, At, B1); PG8_BAR; PG8_SCHED;
	s_add_u32 s10, s8, 0x8000
	s_addc_u32 s11, s9, 0
	s_add_i32 s80, s80, s53
	v_lshl_add_u64 v[252:253], s[10:11], 0, v[142:143]
	s_mov_b32 m0, s80
	ds_read_b128 v[216:219], v175 offset:49152
	ds_read_b128 v[220:223], v175 offset:50176
	ds_read_b128 v[224:227], v175 offset:51200
	ds_read_b128 v[228:231], v175 offset:52224
	ds_read_b128 v[232:235], v175 offset:53248
	ds_read_b128 v[236:239], v175 offset:54272
	ds_read_b128 v[240:243], v175 offset:55296
	ds_read_b128 v[244:247], v175 offset:56320
	global_load_lds_dwordx4 v[252:253], off
	s_add_i32 m0, s80, 0x2000
	s_add_u32 s8, s8, 0xc000
	v_lshl_add_u64 v[252:253], s[10:11], 0, v[146:147]
	s_addc_u32 s9, s9, 0
	s_add_i32 s10, s81, s53
	global_load_lds_dwordx4 v[252:253], off
	v_lshl_add_u64 v[252:253], s[8:9], 0, v[142:143]
	s_mov_b32 m0, s10
	v_lshl_add_u64 v[248:249], v[248:249], 0, s[78:79]
	global_load_lds_dwordx4 v[252:253], off
	v_lshl_add_u64 v[252:253], s[8:9], 0, v[146:147]
	s_add_i32 m0, s10, 0x2000
	s_nop 0
	global_load_lds_dwordx4 v[252:253], off
	s_mov_b32 m0, s63
	s_nop 0
	global_load_lds_dwordx4 v[248:249], off
	v_lshl_add_u64 v[248:249], v[250:251], 0, s[78:79]
	s_mov_b32 m0, s64
	s_nop 0
	global_load_lds_dwordx4 v[248:249], off
	s_waitcnt vmcnt(8)
	s_waitcnt lgkmcnt(0)
	s_barrier
	s_setprio 1
	s_waitcnt lgkmcnt(0)
	v_mfma_f32_16x16x32_bf16 v[62:65], v[130:133], v[216:219], v[62:65]
	v_mfma_f32_16x16x32_bf16 v[58:61], v[138:141], v[216:219], v[58:61]
	v_mfma_f32_16x16x32_bf16 v[46:49], v[130:133], v[224:227], v[46:49]
	v_mfma_f32_16x16x32_bf16 v[42:45], v[138:141], v[224:227], v[42:45]
	v_mfma_f32_16x16x32_bf16 v[30:33], v[130:133], v[232:235], v[30:33]
	v_mfma_f32_16x16x32_bf16 v[26:29], v[138:141], v[232:235], v[26:29]
	v_mfma_f32_16x16x32_bf16 v[14:17], v[130:133], v[240:243], v[14:17]
	v_mfma_f32_16x16x32_bf16 v[10:13], v[138:141], v[240:243], v[10:13]
	v_mfma_f32_16x16x32_bf16 v[62:65], v[134:137], v[220:223], v[62:65]
	v_mfma_f32_16x16x32_bf16 v[58:61], v[154:157], v[220:223], v[58:61]
	v_mfma_f32_16x16x32_bf16 v[46:49], v[134:137], v[228:231], v[46:49]
	v_mfma_f32_16x16x32_bf16 v[42:45], v[154:157], v[228:231], v[42:45]
	v_mfma_f32_16x16x32_bf16 v[30:33], v[134:137], v[236:239], v[30:33]
	v_mfma_f32_16x16x32_bf16 v[26:29], v[154:157], v[236:239], v[26:29]
	v_mfma_f32_16x16x32_bf16 v[14:17], v[134:137], v[244:247], v[14:17]
	v_mfma_f32_16x16x32_bf16 v[10:13], v[154:157], v[244:247], v[10:13]
	s_setprio 0
	s_setprio 1
	v_mfma_f32_16x16x32_bf16 v[54:57], v[176:179], v[216:219], v[54:57]
	v_mfma_f32_16x16x32_bf16 v[50:53], v[184:187], v[216:219], v[50:53]
	v_mfma_f32_16x16x32_bf16 v[38:41], v[176:179], v[224:227], v[38:41]
	v_mfma_f32_16x16x32_bf16 v[34:37], v[184:187], v[224:227], v[34:37]
	v_mfma_f32_16x16x32_bf16 v[22:25], v[176:179], v[232:235], v[22:25]
	v_mfma_f32_16x16x32_bf16 v[18:21], v[184:187], v[232:235], v[18:21]
	v_mfma_f32_16x16x32_bf16 v[6:9], v[176:179], v[240:243], v[6:9]
	v_mfma_f32_16x16x32_bf16 v[2:5], v[184:187], v[240:243], v[2:5]
	v_mfma_f32_16x16x32_bf16 v[54:57], v[180:183], v[220:223], v[54:57]
	v_mfma_f32_16x16x32_bf16 v[50:53], v[188:191], v[220:223], v[50:53]
	v_mfma_f32_16x16x32_bf16 v[38:41], v[180:183], v[228:231], v[38:41]
	v_mfma_f32_16x16x32_bf16 v[34:37], v[188:191], v[228:231], v[34:37]
	v_mfma_f32_16x16x32_bf16 v[22:25], v[180:183], v[236:239], v[22:25]
	v_mfma_f32_16x16x32_bf16 v[18:21], v[188:191], v[236:239], v[18:21]
	v_mfma_f32_16x16x32_bf16 v[6:9], v[180:183], v[244:247], v[6:9]
	v_mfma_f32_16x16x32_bf16 v[2:5], v[188:191], v[244:247], v[2:5]
	s_setprio 0
	s_barrier
	s_add_i32 s43, s43, 2
	s_add_u32 s41, s41, 0x10000
	s_addc_u32 s42, s42, 0
	s_add_u32 s0, s0, 0x100
	s_addc_u32 s1, s1, 0
	.p2align	6

; #define SBAR() __builtin_amdgcn_sched_barrier(0)
; #define VMW() asm volatile("s_waitcnt vmcnt(0)" ::: "memory")
; #define SWRITE_H(bf) do { *(LAS bf16x8*)(V_lds + (bf) * SHM_V + vst0) = st_v0; *(LAS bf16x8*)(V_lds + (bf) * SHM_V + vst1) = st_v1; \
;                           *(LAS bf16x8*)(K_lds + (bf) * SHM_K + kws) = st_k0; *(LAS bf16x8*)(K_lds + (bf) * SHM_K + kws + 32 * 256) = st_k1; } while (0)
; #define MASKT(P0_, P1_, t) do { const int kb_ = KBASE(t); bias_tile(P0_, P1_, Cs + kb_); if (kb_ + KVBLK - 1 > qlo) mask_tile(P0_, P1_, qm - kb_); } while (0)
; __device__ __forceinline__ void partialSM(f32x16& p0, f32x16& p1, float& m_reg, float& alpha) {
;     float pmax = p0[0];
; #pragma unroll
;     for (int r = 1; r < 16; ++r) pmax = fmaxf(pmax, p0[r]);
; #pragma unroll
;     for (int r = 0; r < 16; ++r) pmax = fmaxf(pmax, p1[r]);
;     { auto rr = __builtin_amdgcn_permlane32_swap(__float_as_uint(pmax), __float_as_uint(pmax), false, false);
;       pmax = fmaxf(__uint_as_float(rr[0]), __uint_as_float(rr[1])); }
;     float mn;
;     if (__builtin_expect(__all(pmax - m_reg <= THR2), 1)) { mn = m_reg; alpha = 1.f; }
;     else { mn = fmaxf(m_reg, pmax); alpha = __builtin_amdgcn_exp2f(m_reg - mn); m_reg = mn; }
; #pragma unroll
;     for (int r = 0; r < 16; ++r) p0[r] = p0[r] - mn;
; #pragma unroll
;     for (int r = 0; r < 16; ++r) p1[r] = p1[r] - mn;
; #pragma unroll
;     for (int r = 0; r < 16; ++r) p0[r] = __builtin_amdgcn_exp2f(p0[r]);
; }
; __device__ __forceinline__ void block(const BlockRef& cur, const int j0, const int NT, const int split, const SplitRef sp, lptr lds, int tid) {
;     ...
;     f32x16 pA0, pA1, pB0, pB1; float alA, alB; bf16x8 pa0, pa1, pa2, pa3;
;     SBAR(); qkt<0>(pA0, pA1, K_lds, r32, hi, qr);
;     MASKT(pA0, pA1, 0); partialSM(pA0, pA1, m_reg, alA);
;     VMW(); SWRITE_H(1);
;     __syncthreads();
.LBB0_863:
	v_lshlrev_b32_e32 v51, 3, v216
	v_and_b32_e32 v1, 0xc0, v1
	v_lshlrev_b32_e32 v52, 1, v216
	v_and_or_b32 v1, v51, 24, v1
	v_and_b32_e32 v52, 32, v52
	v_and_b32_e32 v51, 0x100, v51
	v_or3_b32 v1, v1, v52, v51
	v_add_u32_e32 v181, 0, v1
	v_max_f32_e32 v1, v19, v19
	v_max_f32_e32 v51, v18, v18
	v_max_f32_e32 v1, v51, v1
	v_max3_f32 v1, v1, v20, v21
	v_max3_f32 v1, v1, v22, v23
	v_max3_f32 v1, v1, v24, v25
	v_max3_f32 v1, v1, v26, v27
	v_max3_f32 v1, v1, v28, v29
	v_max3_f32 v1, v1, v30, v31
	v_max3_f32 v1, v1, v32, v33
	v_max3_f32 v1, v1, v2, v3
	v_max3_f32 v1, v1, v4, v5
	v_max3_f32 v1, v1, v6, v7
	v_max3_f32 v1, v1, v8, v9
	v_max3_f32 v1, v1, v10, v11
	v_max3_f32 v1, v1, v12, v13
	v_max3_f32 v1, v1, v14, v15
	s_sub_i32 s10, s1, s81
	v_max3_f32 v1, v1, v16, v17
	s_and_b64 s[8:9], s[6:7], exec
	v_mov_b32_e32 v51, v1
	s_cselect_b32 s10, s81, s10
	s_and_b64 s[8:9], s[90:91], exec
	v_permlane32_swap_b32_e32 v1, v51
	s_cselect_b32 s81, s10, s1
	s_and_b32 s1, s85, 0x3fffffc0
	v_max_f32_e32 v51, v51, v51
	v_max_f32_e32 v1, v1, v1
	s_lshl_b32 s1, s1, 2
	v_max_f32_e32 v1, v1, v51
	s_add_i32 s1, s1, 0
	v_add_f32_e32 v51, 0x7149f2ca, v1
	s_add_i32 s1, s1, 0x10000
	v_cmp_ge_f32_e32 vcc, s84, v51
	s_cmp_eq_u64 vcc, exec
	v_max_f32_e32 v1, 0xf149f2ca, v1
	s_cselect_b64 vcc, -1, 0
	v_mov_b32_e32 v52, 0xf149f2ca
	v_sub_f32_e32 v51, 0xf149f2ca, v1
	v_cndmask_b32_e32 v220, v1, v52, vcc
	v_exp_f32_e32 v51, v51
	v_sub_f32_e32 v1, v18, v220
	v_sub_f32_e32 v18, v19, v220
	v_sub_f32_e32 v19, v20, v220
	v_sub_f32_e32 v20, v21, v220
	v_sub_f32_e32 v21, v22, v220
	v_sub_f32_e32 v22, v23, v220
	v_sub_f32_e32 v23, v24, v220
	v_sub_f32_e32 v24, v25, v220
	v_sub_f32_e32 v25, v26, v220
	v_sub_f32_e32 v26, v27, v220
	v_sub_f32_e32 v27, v28, v220
	v_sub_f32_e32 v28, v29, v220
	v_sub_f32_e32 v29, v30, v220
	v_sub_f32_e32 v30, v31, v220
	v_sub_f32_e32 v31, v32, v220
	v_sub_f32_e32 v32, v33, v220
	v_exp_f32_e32 v160, v1
	v_exp_f32_e32 v227, v18
	v_exp_f32_e32 v158, v19
	v_exp_f32_e32 v161, v20
	v_exp_f32_e32 v157, v21
	v_exp_f32_e32 v159, v22
	v_exp_f32_e32 v155, v23
	v_exp_f32_e32 v156, v24
	v_exp_f32_e32 v152, v25
	v_exp_f32_e32 v154, v26
	v_exp_f32_e32 v151, v27
	v_exp_f32_e32 v153, v28
	v_exp_f32_e32 v148, v29
	v_exp_f32_e32 v150, v30
	v_exp_f32_e32 v147, v31
	v_exp_f32_e32 v149, v32
	s_waitcnt vmcnt(0)
	v_cndmask_b32_e64 v191, v51, 1.0, vcc
	v_sub_f32_e32 v67, v17, v220
	v_sub_f32_e32 v66, v16, v220
	v_sub_f32_e32 v69, v15, v220
	v_sub_f32_e32 v68, v14, v220
	v_sub_f32_e32 v71, v13, v220
	v_sub_f32_e32 v70, v12, v220
	v_sub_f32_e32 v73, v11, v220
	v_sub_f32_e32 v72, v10, v220
	v_sub_f32_e32 v75, v9, v220
	v_sub_f32_e32 v74, v8, v220
	v_sub_f32_e32 v77, v7, v220
	v_sub_f32_e32 v76, v6, v220
	v_sub_f32_e32 v79, v5, v220
	v_sub_f32_e32 v78, v4, v220
	s_cmp_lt_i32 s81, 3
	v_cmp_gt_u32_e64 s[8:9], 32, v216
	v_lshl_add_u32 v218, v175, 2, s1
	v_sub_f32_e32 v1, v3, v220
	v_sub_f32_e32 v80, v2, v220
	v_mov_b32_e32 v17, 0
	s_waitcnt vmcnt(3)
	ds_write_b128 v188, v[34:37] offset:16384
	s_waitcnt vmcnt(1)
	ds_write_b128 v189, v[38:41] offset:16384
	ds_write_b128 v190, v[42:45] offset:49152
	s_waitcnt vmcnt(0)
	ds_write_b128 v190, v[46:49] offset:57344
	s_waitcnt lgkmcnt(0)
	s_barrier
	s_cbranch_scc1 .LBB0_883
	s_add_i32 s10, s80, 0xffffff80
	v_add_u32_e32 v2, s10, v219
	s_lshr_b32 s11, s89, 1
	v_sub_u32_e32 v2, v2, v175
	s_lshl_b32 s10, s92, 6
	s_lshl_b32 s12, s11, 7
	v_subrev_u32_e32 v2, s10, v2
	s_add_i32 s10, s12, s10
	s_add_i32 s89, s10, 0x7f
	s_lshl_b32 s10, s11, 9
	s_lshl_b32 s11, s92, 8
	s_add_i32 s10, s10, s11
	s_add_i32 s10, s10, 0
	s_add_i32 s10, s10, 0x10900
	v_mov_b32_e32 v51, v163
	v_add_u32_e32 v223, s10, v162
	v_mov_b32_e32 v162, 0
	v_lshl_add_u64 v[176:177], s[40:41], 0, v[50:51]
	v_lshl_add_u64 v[178:179], s[72:73], 0, v[50:51]
	s_mov_b32 s88, 2
	v_lshl_add_u32 v221, v219, 2, s1
	v_subrev_u32_e32 v222, s12, v2
	v_mov_b32_e32 v50, 0
	v_mov_b32_e32 v51, v162
	v_mov_b32_e32 v52, v162
	v_mov_b32_e32 v53, v162
	v_mov_b32_e32 v54, v162
	v_mov_b32_e32 v55, v162
	v_mov_b32_e32 v56, v162
	v_mov_b32_e32 v57, v162
	v_mov_b32_e32 v58, v162
	v_mov_b32_e32 v59, v162
	v_mov_b32_e32 v60, v162
	v_mov_b32_e32 v61, v162
	v_mov_b32_e32 v62, v162
	v_mov_b32_e32 v63, v162
	v_mov_b32_e32 v64, v162
	v_mov_b32_e32 v65, v162
	v_mov_b32_e32 v34, 0
	v_mov_b32_e32 v35, v162
	v_mov_b32_e32 v36, v162
	v_mov_b32_e32 v37, v162
	v_mov_b32_e32 v38, v162
	v_mov_b32_e32 v39, v162
	v_mov_b32_e32 v40, v162
	v_mov_b32_e32 v41, v162
	v_mov_b32_e32 v42, v162
	v_mov_b32_e32 v43, v162
	v_mov_b32_e32 v44, v162
	v_mov_b32_e32 v45, v162
	v_mov_b32_e32 v46, v162
	v_mov_b32_e32 v47, v162
	v_mov_b32_e32 v48, v162
	v_mov_b32_e32 v49, v162
	v_mov_b32_e32 v18, 0
	v_mov_b32_e32 v19, v162
	v_mov_b32_e32 v20, v162
	v_mov_b32_e32 v21, v162
	v_mov_b32_e32 v22, v162
	v_mov_b32_e32 v23, v162
	v_mov_b32_e32 v24, v162
	v_mov_b32_e32 v25, v162
	v_mov_b32_e32 v26, v162
	v_mov_b32_e32 v27, v162
	v_mov_b32_e32 v28, v162
	v_mov_b32_e32 v29, v162
	v_mov_b32_e32 v30, v162
	v_mov_b32_e32 v31, v162
	v_mov_b32_e32 v32, v162
	v_mov_b32_e32 v33, v162
	v_mov_b32_e32 v2, 0
	v_mov_b32_e32 v3, v162
	v_mov_b32_e32 v4, v162
	v_mov_b32_e32 v5, v162
	v_mov_b32_e32 v6, v162
	v_mov_b32_e32 v7, v162
	v_mov_b32_e32 v8, v162
	v_mov_b32_e32 v9, v162
	v_mov_b32_e32 v10, v162
	v_mov_b32_e32 v11, v162
	v_mov_b32_e32 v12, v162
	v_mov_b32_e32 v13, v162
	v_mov_b32_e32 v14, v162
	v_mov_b32_e32 v15, v162
	v_mov_b32_e32 v16, v162
	v_mov_b32_e32 v17, v162
	s_mov_b32 s92, 0x90000
	.p2align	6

; #define PG8_STAGE(bufoff, gbase, voff) do { _Pragma("unroll") for (int _i = 0; _i < 2; ++_i) \
;         __builtin_amdgcn_global_load_lds((const unsigned*)((const char*)(gbase) + (voff)[_i]), (PG8_LAS unsigned*)(lds + (bufoff) + ldsw + _i * 8192), 16, 0, 0); } while (0)
; #define PG8_LDA(dst, b, h) do { _Pragma("unroll") for (int m = 0; m < 4; ++m) _Pragma("unroll") for (int k = 0; k < 2; ++k) dst[m][k] = *(const PG8_LAS frag_t*)(lds + PG8_SA(b, h) + aoff + m * 2048 + k * 1024); } while (0)
; #define PG8_LDB(dst, b, h) do { _Pragma("unroll") for (int n = 0; n < 2; ++n) _Pragma("unroll") for (int k = 0; k < 2; ++k) dst[n][k] = *(const PG8_LAS frag_t*)(lds + PG8_SB(b, h) + boff + n * 2048 + k * 1024); } while (0)
; #define PG8_MMA(ai, bj, At, Bt) do { __builtin_amdgcn_s_setprio(1); _Pragma("unroll") for (int m = 0; m < 4; ++m) _Pragma("unroll") for (int n = 0; n < 2; ++n) _Pragma("unroll") for (int k = 0; k < 2; ++k) \
;         acc[ai][bj][m][n] = mma1v<MMAV>(Bt[n][k], At[m][k], acc[ai][bj][m][n]); __builtin_amdgcn_s_setprio(0); } while (0)
; #define PG8_WAIT_V(n) asm volatile("s_waitcnt vmcnt(" #n ")" ::: "memory")
; #define PG8_WAIT_L(n) asm volatile("s_waitcnt lgkmcnt(" #n ")" ::: "memory")
; #define PG8_BAR __builtin_amdgcn_s_barrier()
;     ...
;         const char* nA = has_next ? (const char*)g.A + (size_t)nxt.pm * tstep : cA; const char* nB = has_next ? (const char*)g.Bt + (size_t)nxt.pn * tstep : cB;
;         for (int t = 0; t < nt; t += 2) {
;             const bool last = (t == nt - 2);
;             const char* a1 = cA + (size_t)(t + 1) * kstep;
;             const char* a2 = last ? nA : cA + (size_t)(t + 2) * kstep; const char* b2 = last ? nB : cB + (size_t)(t + 2) * kstepB;
;             const char* a3 = a2 + kstep; const char* b3 = b2 + kstepB;
;             if (last && has_next) S.a_ready(nxt);
;             if constexpr (SP2) {
;             PG8_LDB(B0, 0, 0); PG8_LDB(B1, 0, 1); PG8_SCHED; PG8_LDA(At, 0, 0); PG8_STAGE(PG8_SA(1, 1), a1 + hstep, voffA);
;             PG8_WAIT_V(8); PG8_WAIT_L(0); PG8_BAR; PG8_MMA(0, 0, At, B0); PG8_MMA(0, 1, At, B1); PG8_BAR; PG8_SCHED;
;             PG8_LDA(At, 0, 1); PG8_STAGE(PG8_SB(0, 0), b2, voffB); PG8_STAGE(PG8_SB(0, 1), b2 + hstepB, voffB); PG8_STAGE(PG8_SA(0, 0), a2, voffA);
;             PG8_WAIT_V(8); PG8_WAIT_L(0); PG8_BAR; PG8_MMA(1, 0, At, B0); PG8_MMA(1, 1, At, B1); PG8_BAR; PG8_SCHED;
.LBB0_1023:
	s_ashr_i32 s17, s16, 31
	s_lshl_b64 s[18:19], s[16:17], 20
	s_add_u32 s18, s34, s18
	s_addc_u32 s19, s35, s19
	s_and_b64 s[20:21], s[4:5], exec
	s_cselect_b32 s7, s19, s27
	s_cselect_b32 s17, s18, s26
	s_ashr_i32 s15, s14, 31
	s_lshl_b64 s[20:21], s[14:15], 20
	s_add_u32 s20, s36, s20
	s_addc_u32 s21, s37, s21
	s_and_b64 s[28:29], s[4:5], exec
	s_cselect_b32 s15, s21, s25
	s_cselect_b32 s23, s20, s24
	s_add_u32 s51, s24, 0x10000
	s_addc_u32 s52, s25, 0
	s_add_u32 s24, s26, 0x80080
	s_addc_u32 s25, s27, 0
	s_mov_b32 s53, -2
	s_waitcnt lgkmcnt(0)
	s_add_u32 s26, s24, 0xfff80080
	s_addc_u32 s27, s25, -1
	s_add_i32 s54, 0, 0x10000
	s_cmp_eq_u32 s53, 28
	s_cselect_b32 s29, s7, s27
	s_cselect_b32 s28, s17, s26
	v_add_u32_e32 v148, s54, v151
	s_cselect_b32 s27, s15, s52
	s_cselect_b32 s26, s23, s51
	s_add_i32 s56, 0, 0x14000
	ds_read_b128 v[130:133], v148
	ds_read_b128 v[134:137], v148 offset:1024
	ds_read_b128 v[154:157], v148 offset:2048
	ds_read_b128 v[158:161], v148 offset:3072
	v_add_u32_e32 v148, s56, v151
	ds_read_b128 v[174:177], v148
	ds_read_b128 v[178:181], v148 offset:1024
	ds_read_b128 v[182:185], v148 offset:2048
	ds_read_b128 v[186:189], v148 offset:3072
	v_lshl_add_u64 v[148:149], s[24:25], 0, v[144:145]
	s_add_i32 m0, s39, 0xc000
	ds_read_b128 v[216:219], v152
	ds_read_b128 v[220:223], v152 offset:1024
	ds_read_b128 v[224:227], v152 offset:2048
	ds_read_b128 v[228:231], v152 offset:3072
	ds_read_b128 v[232:235], v152 offset:4096
	ds_read_b128 v[236:239], v152 offset:5120
	ds_read_b128 v[240:243], v152 offset:6144
	ds_read_b128 v[244:247], v152 offset:7168
	global_load_lds_dwordx4 v[148:149], off
	v_lshl_add_u64 v[148:149], s[24:25], 0, v[146:147]
	s_add_i32 m0, s39, 0xe000
	s_nop 0
	global_load_lds_dwordx4 v[148:149], off
	s_waitcnt vmcnt(24)
	s_waitcnt lgkmcnt(0)
	s_barrier
	s_setprio 1
	s_waitcnt lgkmcnt(0)
	v_mfma_f32_16x16x32_bf16 v[126:129], v[130:133], v[216:219], 0
	v_mfma_f32_16x16x32_bf16 v[122:125], v[154:157], v[216:219], 0
	v_mfma_f32_16x16x32_bf16 v[110:113], v[130:133], v[224:227], 0
	v_mfma_f32_16x16x32_bf16 v[106:109], v[154:157], v[224:227], 0
	v_mfma_f32_16x16x32_bf16 v[94:97], v[130:133], v[232:235], 0
	v_mfma_f32_16x16x32_bf16 v[90:93], v[154:157], v[232:235], 0
	v_mfma_f32_16x16x32_bf16 v[78:81], v[130:133], v[240:243], 0
	v_mfma_f32_16x16x32_bf16 v[74:77], v[154:157], v[240:243], 0
	v_mfma_f32_16x16x32_bf16 v[126:129], v[134:137], v[220:223], v[126:129]
	v_mfma_f32_16x16x32_bf16 v[122:125], v[158:161], v[220:223], v[122:125]
	v_mfma_f32_16x16x32_bf16 v[110:113], v[134:137], v[228:231], v[110:113]
	v_mfma_f32_16x16x32_bf16 v[106:109], v[158:161], v[228:231], v[106:109]
	v_mfma_f32_16x16x32_bf16 v[94:97], v[134:137], v[236:239], v[94:97]
	v_mfma_f32_16x16x32_bf16 v[90:93], v[158:161], v[236:239], v[90:93]
	v_mfma_f32_16x16x32_bf16 v[78:81], v[134:137], v[244:247], v[78:81]
	v_mfma_f32_16x16x32_bf16 v[74:77], v[158:161], v[244:247], v[74:77]
	s_setprio 0
	s_setprio 1
	v_mfma_f32_16x16x32_bf16 v[118:121], v[174:177], v[216:219], 0
	v_mfma_f32_16x16x32_bf16 v[114:117], v[182:185], v[216:219], 0
	v_mfma_f32_16x16x32_bf16 v[102:105], v[174:177], v[224:227], 0
	v_mfma_f32_16x16x32_bf16 v[98:101], v[182:185], v[224:227], 0
	v_mfma_f32_16x16x32_bf16 v[86:89], v[174:177], v[232:235], 0
	v_mfma_f32_16x16x32_bf16 v[82:85], v[182:185], v[232:235], 0
	v_mfma_f32_16x16x32_bf16 v[70:73], v[174:177], v[240:243], 0
	v_mfma_f32_16x16x32_bf16 v[66:69], v[182:185], v[240:243], 0
	v_mfma_f32_16x16x32_bf16 v[118:121], v[178:181], v[220:223], v[118:121]
	v_mfma_f32_16x16x32_bf16 v[114:117], v[186:189], v[220:223], v[114:117]
	v_mfma_f32_16x16x32_bf16 v[102:105], v[178:181], v[228:231], v[102:105]
	v_mfma_f32_16x16x32_bf16 v[98:101], v[186:189], v[228:231], v[98:101]
	v_mfma_f32_16x16x32_bf16 v[86:89], v[178:181], v[236:239], v[86:89]
	v_mfma_f32_16x16x32_bf16 v[82:85], v[186:189], v[236:239], v[82:85]
	v_mfma_f32_16x16x32_bf16 v[70:73], v[178:181], v[244:247], v[70:73]
	v_mfma_f32_16x16x32_bf16 v[66:69], v[186:189], v[244:247], v[66:69]
	s_setprio 0
	s_barrier
	s_add_i32 s54, s54, s38
	v_lshl_add_u64 v[148:149], s[26:27], 0, v[138:139]
	s_mov_b32 m0, s54
	ds_read_b128 v[216:219], v152 offset:16384
	ds_read_b128 v[220:223], v152 offset:17408
	ds_read_b128 v[224:227], v152 offset:18432
	ds_read_b128 v[228:231], v152 offset:19456
	ds_read_b128 v[232:235], v152 offset:20480
	ds_read_b128 v[236:239], v152 offset:21504
	ds_read_b128 v[240:243], v152 offset:22528
	ds_read_b128 v[244:247], v152 offset:23552
	global_load_lds_dwordx4 v[148:149], off
	s_add_i32 m0, s54, 0x2000
	s_add_u32 s54, s26, 0x4000
	v_lshl_add_u64 v[148:149], s[26:27], 0, v[142:143]
	s_addc_u32 s55, s27, 0
	s_add_i32 s56, s56, s38
	global_load_lds_dwordx4 v[148:149], off
	v_lshl_add_u64 v[148:149], s[54:55], 0, v[138:139]
	s_mov_b32 m0, s56
	v_lshl_add_u64 v[190:191], s[28:29], 0, v[140:141]
	global_load_lds_dwordx4 v[148:149], off
	v_lshl_add_u64 v[148:149], s[54:55], 0, v[142:143]
	s_add_i32 m0, s56, 0x2000
	s_nop 0
	global_load_lds_dwordx4 v[148:149], off
	v_lshl_add_u64 v[148:149], s[28:29], 0, v[162:163]
	s_mov_b32 m0, s39
	s_nop 0
	global_load_lds_dwordx4 v[148:149], off
	s_mov_b32 m0, s40
	s_nop 0
	global_load_lds_dwordx4 v[190:191], off
	s_waitcnt vmcnt(8)
	s_waitcnt lgkmcnt(0)
	s_barrier
; #define PG8_STAGE(bufoff, gbase, voff) do { _Pragma("unroll") for (int _i = 0; _i < 2; ++_i) \
;         __builtin_amdgcn_global_load_lds((const unsigned*)((const char*)(gbase) + (voff)[_i]), (PG8_LAS unsigned*)(lds + (bufoff) + ldsw + _i * 8192), 16, 0, 0); } while (0)
; #define PG8_LDA(dst, b, h) do { _Pragma("unroll") for (int m = 0; m < 4; ++m) _Pragma("unroll") for (int k = 0; k < 2; ++k) dst[m][k] = *(const PG8_LAS frag_t*)(lds + PG8_SA(b, h) + aoff + m * 2048 + k * 1024); } while (0)
; #define PG8_LDB(dst, b, h) do { _Pragma("unroll") for (int n = 0; n < 2; ++n) _Pragma("unroll") for (int k = 0; k < 2; ++k) dst[n][k] = *(const PG8_LAS frag_t*)(lds + PG8_SB(b, h) + boff + n * 2048 + k * 1024); } while (0)
; #define PG8_MMA(ai, bj, At, Bt) do { __builtin_amdgcn_s_setprio(1); _Pragma("unroll") for (int m = 0; m < 4; ++m) _Pragma("unroll") for (int n = 0; n < 2; ++n) _Pragma("unroll") for (int k = 0; k < 2; ++k) \
;         acc[ai][bj][m][n] = mma1v<MMAV>(Bt[n][k], At[m][k], acc[ai][bj][m][n]); __builtin_amdgcn_s_setprio(0); } while (0)
; #define PG8_WAIT_V(n) asm volatile("s_waitcnt vmcnt(" #n ")" ::: "memory")
; #define PG8_WAIT_L(n) asm volatile("s_waitcnt lgkmcnt(" #n ")" ::: "memory")
; #define PG8_BAR __builtin_amdgcn_s_barrier()
; #define PG8_SCHED __builtin_amdgcn_sched_barrier(0)
;     ...
;             PG8_WAIT_V(8); PG8_WAIT_L(0); PG8_BAR; PG8_MMA(1, 0, At, B0); PG8_MMA(1, 1, At, B1); PG8_BAR; PG8_SCHED;
;             PG8_LDB(B0, 1, 0); PG8_LDB(B1, 1, 1); PG8_SCHED; PG8_LDA(At, 1, 0); PG8_STAGE(PG8_SA(0, 1), a2 + hstep, voffA);
;             PG8_WAIT_V(8); PG8_WAIT_L(0); PG8_BAR; PG8_MMA(0, 0, At, B0); PG8_MMA(0, 1, At, B1); PG8_BAR; PG8_SCHED;
	s_setprio 1
	s_waitcnt lgkmcnt(0)
	v_mfma_f32_16x16x32_bf16 v[62:65], v[130:133], v[216:219], 0
	v_mfma_f32_16x16x32_bf16 v[58:61], v[154:157], v[216:219], 0
	v_mfma_f32_16x16x32_bf16 v[46:49], v[130:133], v[224:227], 0
	v_mfma_f32_16x16x32_bf16 v[42:45], v[154:157], v[224:227], 0
	v_mfma_f32_16x16x32_bf16 v[30:33], v[130:133], v[232:235], 0
	v_mfma_f32_16x16x32_bf16 v[26:29], v[154:157], v[232:235], 0
	v_mfma_f32_16x16x32_bf16 v[14:17], v[130:133], v[240:243], 0
	v_mfma_f32_16x16x32_bf16 v[10:13], v[154:157], v[240:243], 0
	v_mfma_f32_16x16x32_bf16 v[62:65], v[134:137], v[220:223], v[62:65]
	v_mfma_f32_16x16x32_bf16 v[58:61], v[158:161], v[220:223], v[58:61]
	v_mfma_f32_16x16x32_bf16 v[46:49], v[134:137], v[228:231], v[46:49]
	v_mfma_f32_16x16x32_bf16 v[42:45], v[158:161], v[228:231], v[42:45]
	v_mfma_f32_16x16x32_bf16 v[30:33], v[134:137], v[236:239], v[30:33]
	v_mfma_f32_16x16x32_bf16 v[26:29], v[158:161], v[236:239], v[26:29]
	v_mfma_f32_16x16x32_bf16 v[14:17], v[134:137], v[244:247], v[14:17]
	v_mfma_f32_16x16x32_bf16 v[10:13], v[158:161], v[244:247], v[10:13]
	s_setprio 0
	s_setprio 1
	v_mfma_f32_16x16x32_bf16 v[54:57], v[174:177], v[216:219], 0
	v_mfma_f32_16x16x32_bf16 v[50:53], v[182:185], v[216:219], 0
	v_mfma_f32_16x16x32_bf16 v[38:41], v[174:177], v[224:227], 0
	v_mfma_f32_16x16x32_bf16 v[34:37], v[182:185], v[224:227], 0
	v_mfma_f32_16x16x32_bf16 v[22:25], v[174:177], v[232:235], 0
	v_mfma_f32_16x16x32_bf16 v[18:21], v[182:185], v[232:235], 0
	v_mfma_f32_16x16x32_bf16 v[6:9], v[174:177], v[240:243], 0
	v_mfma_f32_16x16x32_bf16 v[2:5], v[182:185], v[240:243], 0
	v_mfma_f32_16x16x32_bf16 v[54:57], v[178:181], v[220:223], v[54:57]
	v_mfma_f32_16x16x32_bf16 v[50:53], v[186:189], v[220:223], v[50:53]
	v_mfma_f32_16x16x32_bf16 v[38:41], v[178:181], v[228:231], v[38:41]
	v_mfma_f32_16x16x32_bf16 v[34:37], v[186:189], v[228:231], v[34:37]
	v_mfma_f32_16x16x32_bf16 v[22:25], v[178:181], v[236:239], v[22:25]
	v_mfma_f32_16x16x32_bf16 v[18:21], v[186:189], v[236:239], v[18:21]
	v_mfma_f32_16x16x32_bf16 v[6:9], v[178:181], v[244:247], v[6:9]
	v_mfma_f32_16x16x32_bf16 v[2:5], v[186:189], v[244:247], v[2:5]
	s_setprio 0
	s_barrier
	s_add_i32 s54, 0, 0x18000
	v_add_u32_e32 v153, s54, v151
	s_add_i32 s55, 0, 0x1c000
	ds_read_b128 v[130:133], v153
	ds_read_b128 v[134:137], v153 offset:1024
	ds_read_b128 v[154:157], v153 offset:2048
	ds_read_b128 v[158:161], v153 offset:3072
	v_add_u32_e32 v153, s55, v151
	ds_read_b128 v[174:177], v153
	ds_read_b128 v[178:181], v153 offset:1024
	ds_read_b128 v[182:185], v153 offset:2048
	ds_read_b128 v[186:189], v153 offset:3072
	s_add_u32 s28, s28, 0x80000
	s_addc_u32 s29, s29, 0
	s_mov_b32 m0, s41
	v_lshl_add_u64 v[248:249], s[28:29], 0, v[162:163]
	ds_read_b128 v[216:219], v152 offset:32768
	ds_read_b128 v[220:223], v152 offset:33792
	ds_read_b128 v[224:227], v152 offset:34816
	ds_read_b128 v[228:231], v152 offset:35840
	ds_read_b128 v[232:235], v152 offset:36864
	ds_read_b128 v[236:239], v152 offset:37888
	ds_read_b128 v[240:243], v152 offset:38912
	ds_read_b128 v[244:247], v152 offset:39936
	global_load_lds_dwordx4 v[248:249], off
	v_lshl_add_u64 v[248:249], s[28:29], 0, v[140:141]
	s_mov_b32 m0, s42
	s_nop 0
	global_load_lds_dwordx4 v[248:249], off
	s_waitcnt vmcnt(8)
	s_waitcnt lgkmcnt(0)
	s_barrier
	s_setprio 1
	s_waitcnt lgkmcnt(0)
	v_mfma_f32_16x16x32_bf16 v[126:129], v[130:133], v[216:219], v[126:129]
	v_mfma_f32_16x16x32_bf16 v[122:125], v[154:157], v[216:219], v[122:125]
	v_mfma_f32_16x16x32_bf16 v[110:113], v[130:133], v[224:227], v[110:113]
	v_mfma_f32_16x16x32_bf16 v[106:109], v[154:157], v[224:227], v[106:109]
	v_mfma_f32_16x16x32_bf16 v[94:97], v[130:133], v[232:235], v[94:97]
	v_mfma_f32_16x16x32_bf16 v[90:93], v[154:157], v[232:235], v[90:93]
	v_mfma_f32_16x16x32_bf16 v[78:81], v[130:133], v[240:243], v[78:81]
	v_mfma_f32_16x16x32_bf16 v[74:77], v[154:157], v[240:243], v[74:77]
	v_mfma_f32_16x16x32_bf16 v[126:129], v[134:137], v[220:223], v[126:129]
	v_mfma_f32_16x16x32_bf16 v[122:125], v[158:161], v[220:223], v[122:125]
	v_mfma_f32_16x16x32_bf16 v[110:113], v[134:137], v[228:231], v[110:113]
	v_mfma_f32_16x16x32_bf16 v[106:109], v[158:161], v[228:231], v[106:109]
	v_mfma_f32_16x16x32_bf16 v[94:97], v[134:137], v[236:239], v[94:97]
	v_mfma_f32_16x16x32_bf16 v[90:93], v[158:161], v[236:239], v[90:93]
	v_mfma_f32_16x16x32_bf16 v[78:81], v[134:137], v[244:247], v[78:81]
	v_mfma_f32_16x16x32_bf16 v[74:77], v[158:161], v[244:247], v[74:77]
	s_setprio 0
	s_setprio 1
	v_mfma_f32_16x16x32_bf16 v[118:121], v[174:177], v[216:219], v[118:121]
	v_mfma_f32_16x16x32_bf16 v[114:117], v[182:185], v[216:219], v[114:117]
	v_mfma_f32_16x16x32_bf16 v[102:105], v[174:177], v[224:227], v[102:105]
	v_mfma_f32_16x16x32_bf16 v[98:101], v[182:185], v[224:227], v[98:101]
	v_mfma_f32_16x16x32_bf16 v[86:89], v[174:177], v[232:235], v[86:89]
	v_mfma_f32_16x16x32_bf16 v[82:85], v[182:185], v[232:235], v[82:85]
	v_mfma_f32_16x16x32_bf16 v[70:73], v[174:177], v[240:243], v[70:73]
	v_mfma_f32_16x16x32_bf16 v[66:69], v[182:185], v[240:243], v[66:69]
	v_mfma_f32_16x16x32_bf16 v[118:121], v[178:181], v[220:223], v[118:121]
	v_mfma_f32_16x16x32_bf16 v[114:117], v[186:189], v[220:223], v[114:117]
	v_mfma_f32_16x16x32_bf16 v[102:105], v[178:181], v[228:231], v[102:105]
	v_mfma_f32_16x16x32_bf16 v[98:101], v[186:189], v[228:231], v[98:101]
	v_mfma_f32_16x16x32_bf16 v[86:89], v[178:181], v[236:239], v[86:89]
	v_mfma_f32_16x16x32_bf16 v[82:85], v[186:189], v[236:239], v[82:85]
	v_mfma_f32_16x16x32_bf16 v[70:73], v[178:181], v[244:247], v[70:73]
	v_mfma_f32_16x16x32_bf16 v[66:69], v[186:189], v[244:247], v[66:69]
	s_setprio 0
	s_barrier
; #define PG8_STAGE(bufoff, gbase, voff) do { _Pragma("unroll") for (int _i = 0; _i < 2; ++_i) \
;         __builtin_amdgcn_global_load_lds((const unsigned*)((const char*)(gbase) + (voff)[_i]), (PG8_LAS unsigned*)(lds + (bufoff) + ldsw + _i * 8192), 16, 0, 0); } while (0)
; #define PG8_LDA(dst, b, h) do { _Pragma("unroll") for (int m = 0; m < 4; ++m) _Pragma("unroll") for (int k = 0; k < 2; ++k) dst[m][k] = *(const PG8_LAS frag_t*)(lds + PG8_SA(b, h) + aoff + m * 2048 + k * 1024); } while (0)
; #define PG8_MMA(ai, bj, At, Bt) do { __builtin_amdgcn_s_setprio(1); _Pragma("unroll") for (int m = 0; m < 4; ++m) _Pragma("unroll") for (int n = 0; n < 2; ++n) _Pragma("unroll") for (int k = 0; k < 2; ++k) \
;         acc[ai][bj][m][n] = mma1v<MMAV>(Bt[n][k], At[m][k], acc[ai][bj][m][n]); __builtin_amdgcn_s_setprio(0); } while (0)
; #define PG8_WAIT_V(n) asm volatile("s_waitcnt vmcnt(" #n ")" ::: "memory")
; #define PG8_WAIT_L(n) asm volatile("s_waitcnt lgkmcnt(" #n ")" ::: "memory")
; #define PG8_BAR __builtin_amdgcn_s_barrier()
; #define PG8_SCHED __builtin_amdgcn_sched_barrier(0)
;     ...
;         for (int t = 0; t < nt; t += 2) {
;     ...
;             PG8_LDA(At, 1, 1); PG8_STAGE(PG8_SB(1, 0), b3, voffB); PG8_STAGE(PG8_SB(1, 1), b3 + hstepB, voffB); PG8_STAGE(PG8_SA(1, 0), a3, voffA);
;             PG8_WAIT_V(8); PG8_WAIT_L(0); PG8_BAR; PG8_MMA(1, 0, At, B0); PG8_MMA(1, 1, At, B1); PG8_BAR; PG8_SCHED;
	s_add_u32 s28, s26, 0x8000
	s_addc_u32 s29, s27, 0
	s_add_i32 s54, s54, s38
	v_lshl_add_u64 v[248:249], s[28:29], 0, v[138:139]
	s_mov_b32 m0, s54
	ds_read_b128 v[216:219], v152 offset:49152
	ds_read_b128 v[220:223], v152 offset:50176
	ds_read_b128 v[224:227], v152 offset:51200
	ds_read_b128 v[228:231], v152 offset:52224
	ds_read_b128 v[232:235], v152 offset:53248
	ds_read_b128 v[236:239], v152 offset:54272
	ds_read_b128 v[240:243], v152 offset:55296
	ds_read_b128 v[244:247], v152 offset:56320
	global_load_lds_dwordx4 v[248:249], off
	s_add_i32 m0, s54, 0x2000
	s_add_u32 s26, s26, 0xc000
	v_lshl_add_u64 v[248:249], s[28:29], 0, v[142:143]
	s_addc_u32 s27, s27, 0
	s_add_i32 s28, s55, s38
	global_load_lds_dwordx4 v[248:249], off
	v_lshl_add_u64 v[248:249], s[26:27], 0, v[138:139]
	s_mov_b32 m0, s28
	v_lshl_add_u64 v[148:149], v[148:149], 0, s[78:79]
	global_load_lds_dwordx4 v[248:249], off
	v_lshl_add_u64 v[248:249], s[26:27], 0, v[142:143]
	s_add_i32 m0, s28, 0x2000
	s_nop 0
	global_load_lds_dwordx4 v[248:249], off
	s_mov_b32 m0, s46
	s_nop 0
	global_load_lds_dwordx4 v[148:149], off
	v_lshl_add_u64 v[148:149], v[190:191], 0, s[78:79]
	s_mov_b32 m0, s47
	s_nop 0
	global_load_lds_dwordx4 v[148:149], off
	s_waitcnt vmcnt(8)
	s_waitcnt lgkmcnt(0)
	s_barrier
	s_setprio 1
	s_waitcnt lgkmcnt(0)
	v_mfma_f32_16x16x32_bf16 v[62:65], v[130:133], v[216:219], v[62:65]
	v_mfma_f32_16x16x32_bf16 v[58:61], v[154:157], v[216:219], v[58:61]
	v_mfma_f32_16x16x32_bf16 v[46:49], v[130:133], v[224:227], v[46:49]
	v_mfma_f32_16x16x32_bf16 v[42:45], v[154:157], v[224:227], v[42:45]
	v_mfma_f32_16x16x32_bf16 v[30:33], v[130:133], v[232:235], v[30:33]
	v_mfma_f32_16x16x32_bf16 v[26:29], v[154:157], v[232:235], v[26:29]
	v_mfma_f32_16x16x32_bf16 v[14:17], v[130:133], v[240:243], v[14:17]
	v_mfma_f32_16x16x32_bf16 v[10:13], v[154:157], v[240:243], v[10:13]
	v_mfma_f32_16x16x32_bf16 v[62:65], v[134:137], v[220:223], v[62:65]
	v_mfma_f32_16x16x32_bf16 v[58:61], v[158:161], v[220:223], v[58:61]
	v_mfma_f32_16x16x32_bf16 v[46:49], v[134:137], v[228:231], v[46:49]
	v_mfma_f32_16x16x32_bf16 v[42:45], v[158:161], v[228:231], v[42:45]
	v_mfma_f32_16x16x32_bf16 v[30:33], v[134:137], v[236:239], v[30:33]
	v_mfma_f32_16x16x32_bf16 v[26:29], v[158:161], v[236:239], v[26:29]
	v_mfma_f32_16x16x32_bf16 v[14:17], v[134:137], v[244:247], v[14:17]
	v_mfma_f32_16x16x32_bf16 v[10:13], v[158:161], v[244:247], v[10:13]
	s_setprio 0
	s_setprio 1
	v_mfma_f32_16x16x32_bf16 v[54:57], v[174:177], v[216:219], v[54:57]
	v_mfma_f32_16x16x32_bf16 v[50:53], v[182:185], v[216:219], v[50:53]
	v_mfma_f32_16x16x32_bf16 v[38:41], v[174:177], v[224:227], v[38:41]
	v_mfma_f32_16x16x32_bf16 v[34:37], v[182:185], v[224:227], v[34:37]
	v_mfma_f32_16x16x32_bf16 v[22:25], v[174:177], v[232:235], v[22:25]
	v_mfma_f32_16x16x32_bf16 v[18:21], v[182:185], v[232:235], v[18:21]
	v_mfma_f32_16x16x32_bf16 v[6:9], v[174:177], v[240:243], v[6:9]
	v_mfma_f32_16x16x32_bf16 v[2:5], v[182:185], v[240:243], v[2:5]
	v_mfma_f32_16x16x32_bf16 v[54:57], v[178:181], v[220:223], v[54:57]
	v_mfma_f32_16x16x32_bf16 v[50:53], v[186:189], v[220:223], v[50:53]
	v_mfma_f32_16x16x32_bf16 v[38:41], v[178:181], v[228:231], v[38:41]
	v_mfma_f32_16x16x32_bf16 v[34:37], v[186:189], v[228:231], v[34:37]
	v_mfma_f32_16x16x32_bf16 v[22:25], v[178:181], v[236:239], v[22:25]
	v_mfma_f32_16x16x32_bf16 v[18:21], v[186:189], v[236:239], v[18:21]
	v_mfma_f32_16x16x32_bf16 v[6:9], v[178:181], v[244:247], v[6:9]
	v_mfma_f32_16x16x32_bf16 v[2:5], v[186:189], v[244:247], v[2:5]
	s_setprio 0
	s_barrier
	s_add_i32 s53, s53, 2
	s_add_u32 s51, s51, 0x10000
	s_addc_u32 s52, s52, 0
	s_add_u32 s24, s24, 0x100
	s_addc_u32 s25, s25, 0
	.p2align	6

; #define PG8_STAGE(bufoff, gbase, voff) do { _Pragma("unroll") for (int _i = 0; _i < 2; ++_i) \
;         __builtin_amdgcn_global_load_lds((const unsigned*)((const char*)(gbase) + (voff)[_i]), (PG8_LAS unsigned*)(lds + (bufoff) + ldsw + _i * 8192), 16, 0, 0); } while (0)
; #define PG8_LDA(dst, b, h) do { _Pragma("unroll") for (int m = 0; m < 4; ++m) _Pragma("unroll") for (int k = 0; k < 2; ++k) dst[m][k] = *(const PG8_LAS frag_t*)(lds + PG8_SA(b, h) + aoff + m * 2048 + k * 1024); } while (0)
; #define PG8_LDB(dst, b, h) do { _Pragma("unroll") for (int n = 0; n < 2; ++n) _Pragma("unroll") for (int k = 0; k < 2; ++k) dst[n][k] = *(const PG8_LAS frag_t*)(lds + PG8_SB(b, h) + boff + n * 2048 + k * 1024); } while (0)
; #define PG8_MMA(ai, bj, At, Bt) do { __builtin_amdgcn_s_setprio(1); _Pragma("unroll") for (int m = 0; m < 4; ++m) _Pragma("unroll") for (int n = 0; n < 2; ++n) _Pragma("unroll") for (int k = 0; k < 2; ++k) \
;         acc[ai][bj][m][n] = mma1v<MMAV>(Bt[n][k], At[m][k], acc[ai][bj][m][n]); __builtin_amdgcn_s_setprio(0); } while (0)
; #define PG8_WAIT_V(n) asm volatile("s_waitcnt vmcnt(" #n ")" ::: "memory")
; #define PG8_WAIT_L(n) asm volatile("s_waitcnt lgkmcnt(" #n ")" ::: "memory")
; #define PG8_BAR __builtin_amdgcn_s_barrier()
;     ...
;         const char* nA = has_next ? (const char*)g.A + (size_t)nxt.pm * tstep : cA; const char* nB = has_next ? (const char*)g.Bt + (size_t)nxt.pn * tstep : cB;
;         for (int t = 0; t < nt; t += 2) {
;             const bool last = (t == nt - 2);
;             const char* a1 = cA + (size_t)(t + 1) * kstep;
;             const char* a2 = last ? nA : cA + (size_t)(t + 2) * kstep; const char* b2 = last ? nB : cB + (size_t)(t + 2) * kstepB;
;             const char* a3 = a2 + kstep; const char* b3 = b2 + kstepB;
;             if (last && has_next) S.a_ready(nxt);
;             if constexpr (SP2) {
;             PG8_LDB(B0, 0, 0); PG8_LDB(B1, 0, 1); PG8_SCHED; PG8_LDA(At, 0, 0); PG8_STAGE(PG8_SA(1, 1), a1 + hstep, voffA);
;             PG8_WAIT_V(8); PG8_WAIT_L(0); PG8_BAR; PG8_MMA(0, 0, At, B0); PG8_MMA(0, 1, At, B1); PG8_BAR; PG8_SCHED;
;             PG8_LDA(At, 0, 1); PG8_STAGE(PG8_SB(0, 0), b2, voffB); PG8_STAGE(PG8_SB(0, 1), b2 + hstepB, voffB); PG8_STAGE(PG8_SA(0, 0), a2, voffA);
;             PG8_WAIT_V(8); PG8_WAIT_L(0); PG8_BAR; PG8_MMA(1, 0, At, B0); PG8_MMA(1, 1, At, B1); PG8_BAR; PG8_SCHED;
.LBB0_1223:
	s_add_u32 s6, s20, 0xc000
	s_addc_u32 s7, s21, 0
	s_add_u32 s49, s18, 0x10000
	s_addc_u32 s50, s19, 0
	s_mov_b32 s51, -2
	s_waitcnt lgkmcnt(0)
	s_add_u32 s18, s6, 0x4000
	s_addc_u32 s19, s7, 0
	s_cmpk_eq_i32 s51, 0x54
	s_cselect_b32 s22, s14, s18
	s_cselect_b32 s23, s15, s19
	s_cselect_b32 s20, s16, s49
	s_cselect_b32 s21, s17, s50
	s_add_u32 s18, s22, 0x8000
	s_addc_u32 s19, s23, 0
	s_add_i32 s52, 0, 0x10000
	v_add_u32_e32 v148, s52, v151
	s_add_i32 s54, 0, 0x14000
	ds_read_b128 v[130:133], v148
	ds_read_b128 v[134:137], v148 offset:1024
	ds_read_b128 v[154:157], v148 offset:2048
	ds_read_b128 v[158:161], v148 offset:3072
	v_add_u32_e32 v148, s54, v151
	ds_read_b128 v[174:177], v148
	ds_read_b128 v[178:181], v148 offset:1024
	ds_read_b128 v[182:185], v148 offset:2048
	ds_read_b128 v[186:189], v148 offset:3072
	v_lshl_add_u64 v[148:149], s[6:7], 0, v[144:145]
	s_add_i32 m0, s31, 0xc000
	ds_read_b128 v[216:219], v152
	ds_read_b128 v[220:223], v152 offset:1024
	ds_read_b128 v[224:227], v152 offset:2048
	ds_read_b128 v[228:231], v152 offset:3072
	ds_read_b128 v[232:235], v152 offset:4096
	ds_read_b128 v[236:239], v152 offset:5120
	ds_read_b128 v[240:243], v152 offset:6144
	ds_read_b128 v[244:247], v152 offset:7168
	global_load_lds_dwordx4 v[148:149], off
	v_lshl_add_u64 v[148:149], s[6:7], 0, v[146:147]
	s_add_i32 m0, s31, 0xe000
	s_nop 0
	global_load_lds_dwordx4 v[148:149], off
	s_waitcnt vmcnt(24)
	s_waitcnt lgkmcnt(0)
	s_barrier
	s_setprio 1
	s_waitcnt lgkmcnt(0)
	v_mfma_f32_16x16x32_bf16 v[126:129], v[130:133], v[216:219], 0
	v_mfma_f32_16x16x32_bf16 v[122:125], v[154:157], v[216:219], 0
	v_mfma_f32_16x16x32_bf16 v[110:113], v[130:133], v[224:227], 0
	v_mfma_f32_16x16x32_bf16 v[106:109], v[154:157], v[224:227], 0
	v_mfma_f32_16x16x32_bf16 v[94:97], v[130:133], v[232:235], 0
	v_mfma_f32_16x16x32_bf16 v[90:93], v[154:157], v[232:235], 0
	v_mfma_f32_16x16x32_bf16 v[78:81], v[130:133], v[240:243], 0
	v_mfma_f32_16x16x32_bf16 v[74:77], v[154:157], v[240:243], 0
	v_mfma_f32_16x16x32_bf16 v[126:129], v[134:137], v[220:223], v[126:129]
	v_mfma_f32_16x16x32_bf16 v[122:125], v[158:161], v[220:223], v[122:125]
	v_mfma_f32_16x16x32_bf16 v[110:113], v[134:137], v[228:231], v[110:113]
	v_mfma_f32_16x16x32_bf16 v[106:109], v[158:161], v[228:231], v[106:109]
	v_mfma_f32_16x16x32_bf16 v[94:97], v[134:137], v[236:239], v[94:97]
	v_mfma_f32_16x16x32_bf16 v[90:93], v[158:161], v[236:239], v[90:93]
	v_mfma_f32_16x16x32_bf16 v[78:81], v[134:137], v[244:247], v[78:81]
	v_mfma_f32_16x16x32_bf16 v[74:77], v[158:161], v[244:247], v[74:77]
	s_setprio 0
	s_setprio 1
	v_mfma_f32_16x16x32_bf16 v[118:121], v[174:177], v[216:219], 0
	v_mfma_f32_16x16x32_bf16 v[114:117], v[182:185], v[216:219], 0
	v_mfma_f32_16x16x32_bf16 v[102:105], v[174:177], v[224:227], 0
	v_mfma_f32_16x16x32_bf16 v[98:101], v[182:185], v[224:227], 0
	v_mfma_f32_16x16x32_bf16 v[86:89], v[174:177], v[232:235], 0
	v_mfma_f32_16x16x32_bf16 v[82:85], v[182:185], v[232:235], 0
	v_mfma_f32_16x16x32_bf16 v[70:73], v[174:177], v[240:243], 0
	v_mfma_f32_16x16x32_bf16 v[66:69], v[182:185], v[240:243], 0
	v_mfma_f32_16x16x32_bf16 v[118:121], v[178:181], v[220:223], v[118:121]
	v_mfma_f32_16x16x32_bf16 v[114:117], v[186:189], v[220:223], v[114:117]
	v_mfma_f32_16x16x32_bf16 v[102:105], v[178:181], v[228:231], v[102:105]
	v_mfma_f32_16x16x32_bf16 v[98:101], v[186:189], v[228:231], v[98:101]
	v_mfma_f32_16x16x32_bf16 v[86:89], v[178:181], v[236:239], v[86:89]
	v_mfma_f32_16x16x32_bf16 v[82:85], v[186:189], v[236:239], v[82:85]
	v_mfma_f32_16x16x32_bf16 v[70:73], v[178:181], v[244:247], v[70:73]
	v_mfma_f32_16x16x32_bf16 v[66:69], v[186:189], v[244:247], v[66:69]
	s_setprio 0
	s_barrier
	s_add_i32 s52, s52, s30
	v_lshl_add_u64 v[148:149], s[20:21], 0, v[162:163]
	s_mov_b32 m0, s52
	ds_read_b128 v[216:219], v152 offset:16384
	ds_read_b128 v[220:223], v152 offset:17408
	ds_read_b128 v[224:227], v152 offset:18432
	ds_read_b128 v[228:231], v152 offset:19456
	ds_read_b128 v[232:235], v152 offset:20480
	ds_read_b128 v[236:239], v152 offset:21504
	ds_read_b128 v[240:243], v152 offset:22528
	ds_read_b128 v[244:247], v152 offset:23552
	global_load_lds_dwordx4 v[148:149], off
	s_add_i32 m0, s52, 0x2000
	s_add_u32 s52, s20, 0x4000
	v_lshl_add_u64 v[148:149], s[20:21], 0, v[142:143]
	s_addc_u32 s53, s21, 0
	s_add_i32 s54, s54, s30
	global_load_lds_dwordx4 v[148:149], off
	v_lshl_add_u64 v[148:149], s[52:53], 0, v[162:163]
	s_mov_b32 m0, s54
	s_nop 0
	global_load_lds_dwordx4 v[148:149], off
	v_lshl_add_u64 v[148:149], s[52:53], 0, v[142:143]
	s_add_i32 m0, s54, 0x2000
	s_nop 0
	global_load_lds_dwordx4 v[148:149], off
	v_lshl_add_u64 v[148:149], s[22:23], 0, v[138:139]
	s_mov_b32 m0, s31
	s_nop 0
	global_load_lds_dwordx4 v[148:149], off
	v_lshl_add_u64 v[148:149], s[22:23], 0, v[140:141]
	s_mov_b32 m0, s34
	s_nop 0
	global_load_lds_dwordx4 v[148:149], off
	s_waitcnt vmcnt(8)
	s_waitcnt lgkmcnt(0)
	s_barrier
; #define PG8_STAGE(bufoff, gbase, voff) do { _Pragma("unroll") for (int _i = 0; _i < 2; ++_i) \
;         __builtin_amdgcn_global_load_lds((const unsigned*)((const char*)(gbase) + (voff)[_i]), (PG8_LAS unsigned*)(lds + (bufoff) + ldsw + _i * 8192), 16, 0, 0); } while (0)
; #define PG8_LDA(dst, b, h) do { _Pragma("unroll") for (int m = 0; m < 4; ++m) _Pragma("unroll") for (int k = 0; k < 2; ++k) dst[m][k] = *(const PG8_LAS frag_t*)(lds + PG8_SA(b, h) + aoff + m * 2048 + k * 1024); } while (0)
; #define PG8_LDB(dst, b, h) do { _Pragma("unroll") for (int n = 0; n < 2; ++n) _Pragma("unroll") for (int k = 0; k < 2; ++k) dst[n][k] = *(const PG8_LAS frag_t*)(lds + PG8_SB(b, h) + boff + n * 2048 + k * 1024); } while (0)
; #define PG8_MMA(ai, bj, At, Bt) do { __builtin_amdgcn_s_setprio(1); _Pragma("unroll") for (int m = 0; m < 4; ++m) _Pragma("unroll") for (int n = 0; n < 2; ++n) _Pragma("unroll") for (int k = 0; k < 2; ++k) \
;         acc[ai][bj][m][n] = mma1v<MMAV>(Bt[n][k], At[m][k], acc[ai][bj][m][n]); __builtin_amdgcn_s_setprio(0); } while (0)
; #define PG8_WAIT_V(n) asm volatile("s_waitcnt vmcnt(" #n ")" ::: "memory")
; #define PG8_WAIT_L(n) asm volatile("s_waitcnt lgkmcnt(" #n ")" ::: "memory")
; #define PG8_BAR __builtin_amdgcn_s_barrier()
; #define PG8_SCHED __builtin_amdgcn_sched_barrier(0)
;     ...
;             PG8_LDB(B0, 0, 0); PG8_LDB(B1, 0, 1); PG8_SCHED; PG8_LDA(At, 0, 0); PG8_STAGE(PG8_SA(1, 1), a1 + hstep, voffA);
;             PG8_WAIT_V(8); PG8_WAIT_L(0); PG8_BAR; PG8_MMA(0, 0, At, B0); PG8_MMA(0, 1, At, B1); PG8_BAR; PG8_SCHED;
;             PG8_LDA(At, 0, 1); PG8_STAGE(PG8_SB(0, 0), b2, voffB); PG8_STAGE(PG8_SB(0, 1), b2 + hstepB, voffB); PG8_STAGE(PG8_SA(0, 0), a2, voffA);
;             PG8_WAIT_V(8); PG8_WAIT_L(0); PG8_BAR; PG8_MMA(1, 0, At, B0); PG8_MMA(1, 1, At, B1); PG8_BAR; PG8_SCHED;
;             PG8_LDB(B0, 1, 0); PG8_LDB(B1, 1, 1); PG8_SCHED; PG8_LDA(At, 1, 0); PG8_STAGE(PG8_SA(0, 1), a2 + hstep, voffA);
;             PG8_WAIT_V(8); PG8_WAIT_L(0); PG8_BAR; PG8_MMA(0, 0, At, B0); PG8_MMA(0, 1, At, B1); PG8_BAR; PG8_SCHED;
;             PG8_LDA(At, 1, 1); PG8_STAGE(PG8_SB(1, 0), b3, voffB); PG8_STAGE(PG8_SB(1, 1), b3 + hstepB, voffB); PG8_STAGE(PG8_SA(1, 0), a3, voffA);
;             PG8_WAIT_V(8); PG8_WAIT_L(0); PG8_BAR; PG8_MMA(1, 0, At, B0); PG8_MMA(1, 1, At, B1); PG8_BAR; PG8_SCHED;
	s_setprio 1
	s_waitcnt lgkmcnt(0)
	v_mfma_f32_16x16x32_bf16 v[62:65], v[130:133], v[216:219], 0
	v_mfma_f32_16x16x32_bf16 v[58:61], v[154:157], v[216:219], 0
	v_mfma_f32_16x16x32_bf16 v[46:49], v[130:133], v[224:227], 0
	v_mfma_f32_16x16x32_bf16 v[42:45], v[154:157], v[224:227], 0
	v_mfma_f32_16x16x32_bf16 v[30:33], v[130:133], v[232:235], 0
	v_mfma_f32_16x16x32_bf16 v[26:29], v[154:157], v[232:235], 0
	v_mfma_f32_16x16x32_bf16 v[14:17], v[130:133], v[240:243], 0
	v_mfma_f32_16x16x32_bf16 v[10:13], v[154:157], v[240:243], 0
	v_mfma_f32_16x16x32_bf16 v[62:65], v[134:137], v[220:223], v[62:65]
	v_mfma_f32_16x16x32_bf16 v[58:61], v[158:161], v[220:223], v[58:61]
	v_mfma_f32_16x16x32_bf16 v[46:49], v[134:137], v[228:231], v[46:49]
	v_mfma_f32_16x16x32_bf16 v[42:45], v[158:161], v[228:231], v[42:45]
	v_mfma_f32_16x16x32_bf16 v[30:33], v[134:137], v[236:239], v[30:33]
	v_mfma_f32_16x16x32_bf16 v[26:29], v[158:161], v[236:239], v[26:29]
	v_mfma_f32_16x16x32_bf16 v[14:17], v[134:137], v[244:247], v[14:17]
	v_mfma_f32_16x16x32_bf16 v[10:13], v[158:161], v[244:247], v[10:13]
	s_setprio 0
	s_setprio 1
	v_mfma_f32_16x16x32_bf16 v[54:57], v[174:177], v[216:219], 0
	v_mfma_f32_16x16x32_bf16 v[50:53], v[182:185], v[216:219], 0
	v_mfma_f32_16x16x32_bf16 v[38:41], v[174:177], v[224:227], 0
	v_mfma_f32_16x16x32_bf16 v[34:37], v[182:185], v[224:227], 0
	v_mfma_f32_16x16x32_bf16 v[22:25], v[174:177], v[232:235], 0
	v_mfma_f32_16x16x32_bf16 v[18:21], v[182:185], v[232:235], 0
	v_mfma_f32_16x16x32_bf16 v[6:9], v[174:177], v[240:243], 0
	v_mfma_f32_16x16x32_bf16 v[2:5], v[182:185], v[240:243], 0
	v_mfma_f32_16x16x32_bf16 v[54:57], v[178:181], v[220:223], v[54:57]
	v_mfma_f32_16x16x32_bf16 v[50:53], v[186:189], v[220:223], v[50:53]
	v_mfma_f32_16x16x32_bf16 v[38:41], v[178:181], v[228:231], v[38:41]
	v_mfma_f32_16x16x32_bf16 v[34:37], v[186:189], v[228:231], v[34:37]
	v_mfma_f32_16x16x32_bf16 v[22:25], v[178:181], v[236:239], v[22:25]
	v_mfma_f32_16x16x32_bf16 v[18:21], v[186:189], v[236:239], v[18:21]
	v_mfma_f32_16x16x32_bf16 v[6:9], v[178:181], v[244:247], v[6:9]
	v_mfma_f32_16x16x32_bf16 v[2:5], v[186:189], v[244:247], v[2:5]
	s_setprio 0
	s_barrier
	s_add_i32 s52, 0, 0x18000
	v_add_u32_e32 v148, s52, v151
	s_add_i32 s53, 0, 0x1c000
	ds_read_b128 v[130:133], v148
	ds_read_b128 v[134:137], v148 offset:1024
	ds_read_b128 v[154:157], v148 offset:2048
	ds_read_b128 v[158:161], v148 offset:3072
	v_add_u32_e32 v148, s53, v151
	ds_read_b128 v[174:177], v148
	ds_read_b128 v[178:181], v148 offset:1024
	ds_read_b128 v[182:185], v148 offset:2048
	ds_read_b128 v[186:189], v148 offset:3072
	s_add_u32 s22, s22, 0x4000
	s_addc_u32 s23, s23, 0
	s_mov_b32 m0, s35
	v_lshl_add_u64 v[148:149], s[22:23], 0, v[138:139]
	ds_read_b128 v[216:219], v152 offset:32768
	ds_read_b128 v[220:223], v152 offset:33792
	ds_read_b128 v[224:227], v152 offset:34816
	ds_read_b128 v[228:231], v152 offset:35840
	ds_read_b128 v[232:235], v152 offset:36864
	ds_read_b128 v[236:239], v152 offset:37888
	ds_read_b128 v[240:243], v152 offset:38912
	ds_read_b128 v[244:247], v152 offset:39936
	global_load_lds_dwordx4 v[148:149], off
	v_lshl_add_u64 v[148:149], s[22:23], 0, v[140:141]
	s_mov_b32 m0, s36
	s_nop 0
	global_load_lds_dwordx4 v[148:149], off
	s_waitcnt vmcnt(8)
	s_waitcnt lgkmcnt(0)
	s_barrier
	s_setprio 1
	s_waitcnt lgkmcnt(0)
	v_mfma_f32_16x16x32_bf16 v[126:129], v[130:133], v[216:219], v[126:129]
	v_mfma_f32_16x16x32_bf16 v[122:125], v[154:157], v[216:219], v[122:125]
	v_mfma_f32_16x16x32_bf16 v[110:113], v[130:133], v[224:227], v[110:113]
	v_mfma_f32_16x16x32_bf16 v[106:109], v[154:157], v[224:227], v[106:109]
	v_mfma_f32_16x16x32_bf16 v[94:97], v[130:133], v[232:235], v[94:97]
	v_mfma_f32_16x16x32_bf16 v[90:93], v[154:157], v[232:235], v[90:93]
	v_mfma_f32_16x16x32_bf16 v[78:81], v[130:133], v[240:243], v[78:81]
	v_mfma_f32_16x16x32_bf16 v[74:77], v[154:157], v[240:243], v[74:77]
	v_mfma_f32_16x16x32_bf16 v[126:129], v[134:137], v[220:223], v[126:129]
	v_mfma_f32_16x16x32_bf16 v[122:125], v[158:161], v[220:223], v[122:125]
	v_mfma_f32_16x16x32_bf16 v[110:113], v[134:137], v[228:231], v[110:113]
	v_mfma_f32_16x16x32_bf16 v[106:109], v[158:161], v[228:231], v[106:109]
	v_mfma_f32_16x16x32_bf16 v[94:97], v[134:137], v[236:239], v[94:97]
	v_mfma_f32_16x16x32_bf16 v[90:93], v[158:161], v[236:239], v[90:93]
	v_mfma_f32_16x16x32_bf16 v[78:81], v[134:137], v[244:247], v[78:81]
	v_mfma_f32_16x16x32_bf16 v[74:77], v[158:161], v[244:247], v[74:77]
	s_setprio 0
	s_setprio 1
	v_mfma_f32_16x16x32_bf16 v[118:121], v[174:177], v[216:219], v[118:121]
	v_mfma_f32_16x16x32_bf16 v[114:117], v[182:185], v[216:219], v[114:117]
	v_mfma_f32_16x16x32_bf16 v[102:105], v[174:177], v[224:227], v[102:105]
	v_mfma_f32_16x16x32_bf16 v[98:101], v[182:185], v[224:227], v[98:101]
	v_mfma_f32_16x16x32_bf16 v[86:89], v[174:177], v[232:235], v[86:89]
	v_mfma_f32_16x16x32_bf16 v[82:85], v[182:185], v[232:235], v[82:85]
	v_mfma_f32_16x16x32_bf16 v[70:73], v[174:177], v[240:243], v[70:73]
	v_mfma_f32_16x16x32_bf16 v[66:69], v[182:185], v[240:243], v[66:69]
	v_mfma_f32_16x16x32_bf16 v[118:121], v[178:181], v[220:223], v[118:121]
	v_mfma_f32_16x16x32_bf16 v[114:117], v[186:189], v[220:223], v[114:117]
	v_mfma_f32_16x16x32_bf16 v[102:105], v[178:181], v[228:231], v[102:105]
	v_mfma_f32_16x16x32_bf16 v[98:101], v[186:189], v[228:231], v[98:101]
	v_mfma_f32_16x16x32_bf16 v[86:89], v[178:181], v[236:239], v[86:89]
	v_mfma_f32_16x16x32_bf16 v[82:85], v[186:189], v[236:239], v[82:85]
	v_mfma_f32_16x16x32_bf16 v[70:73], v[178:181], v[244:247], v[70:73]
	v_mfma_f32_16x16x32_bf16 v[66:69], v[186:189], v[244:247], v[66:69]
	s_setprio 0
	s_barrier
; #define PG8_STAGE(bufoff, gbase, voff) do { _Pragma("unroll") for (int _i = 0; _i < 2; ++_i) \
;         __builtin_amdgcn_global_load_lds((const unsigned*)((const char*)(gbase) + (voff)[_i]), (PG8_LAS unsigned*)(lds + (bufoff) + ldsw + _i * 8192), 16, 0, 0); } while (0)
; #define PG8_LDA(dst, b, h) do { _Pragma("unroll") for (int m = 0; m < 4; ++m) _Pragma("unroll") for (int k = 0; k < 2; ++k) dst[m][k] = *(const PG8_LAS frag_t*)(lds + PG8_SA(b, h) + aoff + m * 2048 + k * 1024); } while (0)
; #define PG8_LDB(dst, b, h) do { _Pragma("unroll") for (int n = 0; n < 2; ++n) _Pragma("unroll") for (int k = 0; k < 2; ++k) dst[n][k] = *(const PG8_LAS frag_t*)(lds + PG8_SB(b, h) + boff + n * 2048 + k * 1024); } while (0)
; #define PG8_MMA(ai, bj, At, Bt) do { __builtin_amdgcn_s_setprio(1); _Pragma("unroll") for (int m = 0; m < 4; ++m) _Pragma("unroll") for (int n = 0; n < 2; ++n) _Pragma("unroll") for (int k = 0; k < 2; ++k) \
;         acc[ai][bj][m][n] = mma1v<MMAV>(Bt[n][k], At[m][k], acc[ai][bj][m][n]); __builtin_amdgcn_s_setprio(0); } while (0)
; #define PG8_WAIT_V(n) asm volatile("s_waitcnt vmcnt(" #n ")" ::: "memory")
; #define PG8_WAIT_L(n) asm volatile("s_waitcnt lgkmcnt(" #n ")" ::: "memory")
; #define PG8_BAR __builtin_amdgcn_s_barrier()
; #define PG8_SCHED __builtin_amdgcn_sched_barrier(0)
;     ...
;         for (int t = 0; t < nt; t += 2) {
;     ...
;             PG8_LDB(B0, 1, 0); PG8_LDB(B1, 1, 1); PG8_SCHED; PG8_LDA(At, 1, 0); PG8_STAGE(PG8_SA(0, 1), a2 + hstep, voffA);
;             PG8_WAIT_V(8); PG8_WAIT_L(0); PG8_BAR; PG8_MMA(0, 0, At, B0); PG8_MMA(0, 1, At, B1); PG8_BAR; PG8_SCHED;
;             PG8_LDA(At, 1, 1); PG8_STAGE(PG8_SB(1, 0), b3, voffB); PG8_STAGE(PG8_SB(1, 1), b3 + hstepB, voffB); PG8_STAGE(PG8_SA(1, 0), a3, voffA);
;             PG8_WAIT_V(8); PG8_WAIT_L(0); PG8_BAR; PG8_MMA(1, 0, At, B0); PG8_MMA(1, 1, At, B1); PG8_BAR; PG8_SCHED;
	s_add_u32 s22, s20, 0x8000
	s_addc_u32 s23, s21, 0
	s_add_i32 s52, s52, s30
	v_lshl_add_u64 v[148:149], s[22:23], 0, v[162:163]
	s_mov_b32 m0, s52
	ds_read_b128 v[216:219], v152 offset:49152
	ds_read_b128 v[220:223], v152 offset:50176
	ds_read_b128 v[224:227], v152 offset:51200
	ds_read_b128 v[228:231], v152 offset:52224
	ds_read_b128 v[232:235], v152 offset:53248
	ds_read_b128 v[236:239], v152 offset:54272
	ds_read_b128 v[240:243], v152 offset:55296
	ds_read_b128 v[244:247], v152 offset:56320
	global_load_lds_dwordx4 v[148:149], off
	s_add_i32 m0, s52, 0x2000
	s_add_u32 s20, s20, 0xc000
	v_lshl_add_u64 v[148:149], s[22:23], 0, v[142:143]
	s_addc_u32 s21, s21, 0
	s_add_i32 s22, s53, s30
	global_load_lds_dwordx4 v[148:149], off
	v_lshl_add_u64 v[148:149], s[20:21], 0, v[162:163]
	s_mov_b32 m0, s22
	s_nop 0
	global_load_lds_dwordx4 v[148:149], off
	v_lshl_add_u64 v[148:149], s[20:21], 0, v[142:143]
	s_add_i32 m0, s22, 0x2000
	s_nop 0
	global_load_lds_dwordx4 v[148:149], off
	v_lshl_add_u64 v[148:149], s[18:19], 0, v[138:139]
	s_mov_b32 m0, s40
	s_nop 0
	global_load_lds_dwordx4 v[148:149], off
	v_lshl_add_u64 v[148:149], s[18:19], 0, v[140:141]
	s_mov_b32 m0, s41
	s_nop 0
	global_load_lds_dwordx4 v[148:149], off
	s_waitcnt vmcnt(8)
	s_waitcnt lgkmcnt(0)
	s_barrier
	s_setprio 1
	s_waitcnt lgkmcnt(0)
	v_mfma_f32_16x16x32_bf16 v[62:65], v[130:133], v[216:219], v[62:65]
	v_mfma_f32_16x16x32_bf16 v[58:61], v[154:157], v[216:219], v[58:61]
	v_mfma_f32_16x16x32_bf16 v[46:49], v[130:133], v[224:227], v[46:49]
	v_mfma_f32_16x16x32_bf16 v[42:45], v[154:157], v[224:227], v[42:45]
	v_mfma_f32_16x16x32_bf16 v[30:33], v[130:133], v[232:235], v[30:33]
	v_mfma_f32_16x16x32_bf16 v[26:29], v[154:157], v[232:235], v[26:29]
	v_mfma_f32_16x16x32_bf16 v[14:17], v[130:133], v[240:243], v[14:17]
	v_mfma_f32_16x16x32_bf16 v[10:13], v[154:157], v[240:243], v[10:13]
	v_mfma_f32_16x16x32_bf16 v[62:65], v[134:137], v[220:223], v[62:65]
	v_mfma_f32_16x16x32_bf16 v[58:61], v[158:161], v[220:223], v[58:61]
	v_mfma_f32_16x16x32_bf16 v[46:49], v[134:137], v[228:231], v[46:49]
	v_mfma_f32_16x16x32_bf16 v[42:45], v[158:161], v[228:231], v[42:45]
	v_mfma_f32_16x16x32_bf16 v[30:33], v[134:137], v[236:239], v[30:33]
	v_mfma_f32_16x16x32_bf16 v[26:29], v[158:161], v[236:239], v[26:29]
	v_mfma_f32_16x16x32_bf16 v[14:17], v[134:137], v[244:247], v[14:17]
	v_mfma_f32_16x16x32_bf16 v[10:13], v[158:161], v[244:247], v[10:13]
	s_setprio 0
	s_setprio 1
	v_mfma_f32_16x16x32_bf16 v[54:57], v[174:177], v[216:219], v[54:57]
	v_mfma_f32_16x16x32_bf16 v[50:53], v[182:185], v[216:219], v[50:53]
	v_mfma_f32_16x16x32_bf16 v[38:41], v[174:177], v[224:227], v[38:41]
	v_mfma_f32_16x16x32_bf16 v[34:37], v[182:185], v[224:227], v[34:37]
	v_mfma_f32_16x16x32_bf16 v[22:25], v[174:177], v[232:235], v[22:25]
	v_mfma_f32_16x16x32_bf16 v[18:21], v[182:185], v[232:235], v[18:21]
	v_mfma_f32_16x16x32_bf16 v[6:9], v[174:177], v[240:243], v[6:9]
	v_mfma_f32_16x16x32_bf16 v[2:5], v[182:185], v[240:243], v[2:5]
	v_mfma_f32_16x16x32_bf16 v[54:57], v[178:181], v[220:223], v[54:57]
	v_mfma_f32_16x16x32_bf16 v[50:53], v[186:189], v[220:223], v[50:53]
	v_mfma_f32_16x16x32_bf16 v[38:41], v[178:181], v[228:231], v[38:41]
	v_mfma_f32_16x16x32_bf16 v[34:37], v[186:189], v[228:231], v[34:37]
	v_mfma_f32_16x16x32_bf16 v[22:25], v[178:181], v[236:239], v[22:25]
	v_mfma_f32_16x16x32_bf16 v[18:21], v[186:189], v[236:239], v[18:21]
	v_mfma_f32_16x16x32_bf16 v[6:9], v[178:181], v[244:247], v[6:9]
	v_mfma_f32_16x16x32_bf16 v[2:5], v[186:189], v[244:247], v[2:5]
	s_setprio 0
	s_barrier
	s_add_i32 s51, s51, 2
	s_add_u32 s6, s6, 0x10000
	s_addc_u32 s7, s7, 0
	s_add_u32 s49, s49, 0x10000
	s_addc_u32 s50, s50, 0
	.p2align	6
